# v66 + non-temporal hint on the f32 weight loads of the transposes
# speedup vs baseline: 1.0038x; 1.0012x over previous
; #define LAS __attribute__((address_space(3)))
;     if (ldw == 0) ldw = N;
;     LAS float* scr = (LAS float*)(F.lds + F.wave * 16384); const int lane = F.lane;
;     const int nblk = N / 32, nitems = (K / 64) * nblk;
;     for (int item = F.gw; item < nitems; item += F.NGW) { const int kb = item / nblk, nb = item % nblk, k0 = 64 * kb, n0 = 32 * nb;
;         int dr0 = n0; if (MAP == 1) { if (n0 < DFF) dr0 = (n0 >> 7) * 256 + (n0 & 127); else { const int uo = n0 - DFF; dr0 = (uo >> 7) * 256 + 128 + (uo & 127); } }
; #pragma unroll 8
;         for (int i = 0; i < 32; ++i) { const int kk = 2 * i + (lane >> 5); scr[kk * 33 + (lane & 31)] = W[(size_t)(k0 + kk) * ldw + n0 + (lane & 31)]; }
.LBB0_11:
	s_or_b64 exec, exec, s[0:1]
	s_lshr_b32 s0, s86, 6
	s_lshl_b32 s79, s2, 3
	s_add_i32 s94, s0, s79
	s_lshl_b32 s92, s96, 3
	s_cmp_lt_i32 s94, 0xac00
	v_and_b32_e32 v178, 63, v0
	v_writelane_b32 v240, s0, 2
	s_cselect_b64 s[0:1], -1, 0
	v_writelane_b32 v240, s0, 3
	s_cmp_gt_i32 s94, 0xabff
	v_lshrrev_b32_e32 v162, 5, v178
	v_and_b32_e32 v164, 31, v0
	v_lshrrev_b32_e32 v163, 2, v178
	v_lshlrev_b32_e32 v167, 4, v0
	v_and_b32_e32 v165, 60, v178
	v_writelane_b32 v240, s1, 4
	s_cbranch_scc1 .LBB0_20
	s_barrier
	s_load_dwordx2 s[50:51], s[74:75], 0x38
	v_readlane_b32 s16, v240, 2
	v_lshlrev_b32_e32 v212, 4, v178
	v_mov_b32_e32 v216, 0x42fe0000
	s_mov_b32 s36, 0x44fe0000
	s_mov_b32 s37, 0
	s_mov_b32 s38, 0x4b400000
	s_mov_b32 s39, 0
	s_mov_b32 s40, 0xc2fe0000
	s_mov_b32 s41, 0x0c0c0400
	s_mov_b32 s42, 0x05040100
	s_lshl_b32 s17, s16, 5
	s_and_b32 s18, s16, 4
	s_lshl_b32 s18, s18, 5
	s_add_i32 s17, s17, s18
	v_mul_u32_u24_e32 v213, 0x240, v178
	s_lshl_b32 s18, s16, 4
	v_add_u32_e32 v213, s18, v213
	v_lshrrev_b32_e32 v204, 3, v178
	v_and_b32_e32 v205, 7, v178
	s_lshl_b32 s18, s16, 5
	v_add_u32_e32 v206, s18, v204
	v_mul_u32_u24_e32 v214, 0x90, v206
	v_lshl_add_u32 v214, v205, 4, v214
	v_mul_u32_u24_e32 v215, 0x1000, v204
	v_lshl_add_u32 v215, v205, 4, v215
	s_lshl_b32 s16, s16, 4
	s_waitcnt lgkmcnt(0)
	s_add_u32 s44, s90, 0x8300000
	s_addc_u32 s45, s91, 0
	s_mov_b32 s19, s2
	s_cmp_lt_u32 s19, 0xac0
	s_cbranch_scc0 .Lf8t_f1in0_end
	s_mul_hi_u32 s20, s19, 0x2fa0be9
	s_mul_i32 s21, s20, 86
	s_sub_i32 s21, s19, s21
	s_lshl_b32 s60, s20, 7
	s_lshl_b32 s61, s21, 8
	s_add_i32 s24, s60, s16
	s_mul_i32 s24, s24, 0x15800
	s_lshl_b32 s25, s61, 2
	s_add_u32 s24, s24, s25
	s_add_u32 s52, s50, s24
	s_addc_u32 s53, s51, 0
	global_load_dwordx4 v[80:83], v212, s[52:53] nt
	s_add_u32 s52, s52, 0x15800
	s_addc_u32 s53, s53, 0
	global_load_dwordx4 v[84:87], v212, s[52:53] nt
	s_add_u32 s52, s52, 0x15800
	s_addc_u32 s53, s53, 0
	global_load_dwordx4 v[88:91], v212, s[52:53] nt
	s_add_u32 s52, s52, 0x15800
	s_addc_u32 s53, s53, 0
	global_load_dwordx4 v[92:95], v212, s[52:53] nt
	s_add_u32 s52, s52, 0x15800
	s_addc_u32 s53, s53, 0
	global_load_dwordx4 v[96:99], v212, s[52:53] nt
	s_add_u32 s52, s52, 0x15800
	s_addc_u32 s53, s53, 0
	global_load_dwordx4 v[100:103], v212, s[52:53] nt
	s_add_u32 s52, s52, 0x15800
	s_addc_u32 s53, s53, 0
	global_load_dwordx4 v[104:107], v212, s[52:53] nt
	s_add_u32 s52, s52, 0x15800
	s_addc_u32 s53, s53, 0
	global_load_dwordx4 v[108:111], v212, s[52:53] nt
	s_add_u32 s52, s52, 0x15800
	s_addc_u32 s53, s53, 0
	global_load_dwordx4 v[112:115], v212, s[52:53] nt
	s_add_u32 s52, s52, 0x15800
	s_addc_u32 s53, s53, 0
	global_load_dwordx4 v[116:119], v212, s[52:53] nt
	s_add_u32 s52, s52, 0x15800
	s_addc_u32 s53, s53, 0
	global_load_dwordx4 v[120:123], v212, s[52:53] nt
	s_add_u32 s52, s52, 0x15800
	s_addc_u32 s53, s53, 0
	global_load_dwordx4 v[124:127], v212, s[52:53] nt
	s_add_u32 s52, s52, 0x15800
	s_addc_u32 s53, s53, 0
	global_load_dwordx4 v[128:131], v212, s[52:53] nt
	s_add_u32 s52, s52, 0x15800
	s_addc_u32 s53, s53, 0
	global_load_dwordx4 v[132:135], v212, s[52:53] nt
	s_add_u32 s52, s52, 0x15800
	s_addc_u32 s53, s53, 0
	global_load_dwordx4 v[136:139], v212, s[52:53] nt
	s_add_u32 s52, s52, 0x15800
	s_addc_u32 s53, s53, 0
	global_load_dwordx4 v[140:143], v212, s[52:53] nt
	s_mov_b32 s58, 1
.Lf8t_f1in0_loop:
	s_add_i32 s59, s19, s96
	s_cmp_lt_u32 s59, 0xac0
	s_cbranch_scc0 .Lf8t_f1in0_a_nonext
	s_mul_hi_u32 s20, s59, 0x2fa0be9
	s_mul_i32 s21, s20, 86
	s_sub_i32 s21, s59, s21
	s_lshl_b32 s62, s20, 7
	s_lshl_b32 s63, s21, 8
	s_add_i32 s24, s62, s16
	s_mul_i32 s24, s24, 0x15800
	s_lshl_b32 s25, s63, 2
	s_add_u32 s24, s24, s25
	s_add_u32 s52, s50, s24
	s_addc_u32 s53, s51, 0
	global_load_dwordx4 v[16:19], v212, s[52:53] nt
	s_add_u32 s52, s52, 0x15800
	s_addc_u32 s53, s53, 0
	global_load_dwordx4 v[20:23], v212, s[52:53] nt
	s_add_u32 s52, s52, 0x15800
	s_addc_u32 s53, s53, 0
	global_load_dwordx4 v[24:27], v212, s[52:53] nt
	s_add_u32 s52, s52, 0x15800
	s_addc_u32 s53, s53, 0
	global_load_dwordx4 v[28:31], v212, s[52:53] nt
	s_add_u32 s52, s52, 0x15800
	s_addc_u32 s53, s53, 0
	global_load_dwordx4 v[32:35], v212, s[52:53] nt
	s_add_u32 s52, s52, 0x15800
	s_addc_u32 s53, s53, 0
	global_load_dwordx4 v[36:39], v212, s[52:53] nt
	s_add_u32 s52, s52, 0x15800
	s_addc_u32 s53, s53, 0
	global_load_dwordx4 v[40:43], v212, s[52:53] nt
	s_add_u32 s52, s52, 0x15800
	s_addc_u32 s53, s53, 0
	global_load_dwordx4 v[44:47], v212, s[52:53] nt
	s_add_u32 s52, s52, 0x15800
	s_addc_u32 s53, s53, 0
	global_load_dwordx4 v[48:51], v212, s[52:53] nt
	s_add_u32 s52, s52, 0x15800
	s_addc_u32 s53, s53, 0
	global_load_dwordx4 v[52:55], v212, s[52:53] nt
	s_add_u32 s52, s52, 0x15800
	s_addc_u32 s53, s53, 0
	global_load_dwordx4 v[56:59], v212, s[52:53] nt
	s_add_u32 s52, s52, 0x15800
	s_addc_u32 s53, s53, 0
	global_load_dwordx4 v[60:63], v212, s[52:53] nt
	s_add_u32 s52, s52, 0x15800
	s_addc_u32 s53, s53, 0
	global_load_dwordx4 v[64:67], v212, s[52:53] nt
	s_add_u32 s52, s52, 0x15800
	s_addc_u32 s53, s53, 0
	global_load_dwordx4 v[68:71], v212, s[52:53] nt
	s_add_u32 s52, s52, 0x15800
	s_addc_u32 s53, s53, 0
	global_load_dwordx4 v[144:147], v212, s[52:53] nt
	s_add_u32 s52, s52, 0x15800
	s_addc_u32 s53, s53, 0
	global_load_dwordx4 v[148:151], v212, s[52:53] nt
	s_cmp_eq_u32 s58, 1
	s_cbranch_scc1 .Lf8t_f1in0_a_first
	s_waitcnt vmcnt(20)
	s_branch .Lf8t_f1in0_a_go

; __device__ __forceinline__ unsigned pk4_i8(float a, float b, float c, float d, float s) {
;     const unsigned ua = __float_as_uint(__builtin_amdgcn_fmed3f(a * s, -127.f, 127.f) + 12582912.f), ub = __float_as_uint(__builtin_amdgcn_fmed3f(b * s, -127.f, 127.f) + 12582912.f);
;     const unsigned uc = __float_as_uint(__builtin_amdgcn_fmed3f(c * s, -127.f, 127.f) + 12582912.f), ud = __float_as_uint(__builtin_amdgcn_fmed3f(d * s, -127.f, 127.f) + 12582912.f);
;     return (ua & 0xffu) | ((ub & 0xffu) << 8) | ((uc & 0xffu) << 16) | (ud << 24);
;     ...
;             if (QI8) { o.x = pk4_i8(sp[0 * 33], sp[1 * 33], sp[2 * 33], sp[3 * 33], scl); o.y = pk4_i8(sp[4 * 33], sp[5 * 33], sp[6 * 33], sp[7 * 33], scl);
;                 o.z = pk4_i8(sp[8 * 33], sp[9 * 33], sp[10 * 33], sp[11 * 33], scl); o.w = pk4_i8(sp[12 * 33], sp[13 * 33], sp[14 * 33], sp[15 * 33], scl); }
.Lf8t_f1in0_a_go:
	s_mov_b32 s58, 0
	v_pk_mul_f32 v[80:81], v[80:81], s[36:37] op_sel_hi:[1,0]
	v_pk_mul_f32 v[82:83], v[82:83], s[36:37] op_sel_hi:[1,0]
	v_pk_mul_f32 v[84:85], v[84:85], s[36:37] op_sel_hi:[1,0]
	v_pk_mul_f32 v[86:87], v[86:87], s[36:37] op_sel_hi:[1,0]
	v_pk_mul_f32 v[88:89], v[88:89], s[36:37] op_sel_hi:[1,0]
	v_pk_mul_f32 v[90:91], v[90:91], s[36:37] op_sel_hi:[1,0]
	v_pk_mul_f32 v[92:93], v[92:93], s[36:37] op_sel_hi:[1,0]
	v_pk_mul_f32 v[94:95], v[94:95], s[36:37] op_sel_hi:[1,0]
	v_pk_mul_f32 v[96:97], v[96:97], s[36:37] op_sel_hi:[1,0]
	v_pk_mul_f32 v[98:99], v[98:99], s[36:37] op_sel_hi:[1,0]
	v_pk_mul_f32 v[100:101], v[100:101], s[36:37] op_sel_hi:[1,0]
	v_pk_mul_f32 v[102:103], v[102:103], s[36:37] op_sel_hi:[1,0]
	v_pk_mul_f32 v[104:105], v[104:105], s[36:37] op_sel_hi:[1,0]
	v_pk_mul_f32 v[106:107], v[106:107], s[36:37] op_sel_hi:[1,0]
	v_pk_mul_f32 v[108:109], v[108:109], s[36:37] op_sel_hi:[1,0]
	v_pk_mul_f32 v[110:111], v[110:111], s[36:37] op_sel_hi:[1,0]
	v_pk_mul_f32 v[112:113], v[112:113], s[36:37] op_sel_hi:[1,0]
	v_pk_mul_f32 v[114:115], v[114:115], s[36:37] op_sel_hi:[1,0]
	v_pk_mul_f32 v[116:117], v[116:117], s[36:37] op_sel_hi:[1,0]
	v_pk_mul_f32 v[118:119], v[118:119], s[36:37] op_sel_hi:[1,0]
	v_pk_mul_f32 v[120:121], v[120:121], s[36:37] op_sel_hi:[1,0]
	v_pk_mul_f32 v[122:123], v[122:123], s[36:37] op_sel_hi:[1,0]
	v_pk_mul_f32 v[124:125], v[124:125], s[36:37] op_sel_hi:[1,0]
	v_pk_mul_f32 v[126:127], v[126:127], s[36:37] op_sel_hi:[1,0]
	v_pk_mul_f32 v[128:129], v[128:129], s[36:37] op_sel_hi:[1,0]
	v_pk_mul_f32 v[130:131], v[130:131], s[36:37] op_sel_hi:[1,0]
	v_pk_mul_f32 v[132:133], v[132:133], s[36:37] op_sel_hi:[1,0]
	v_pk_mul_f32 v[134:135], v[134:135], s[36:37] op_sel_hi:[1,0]
	v_pk_mul_f32 v[136:137], v[136:137], s[36:37] op_sel_hi:[1,0]
	v_pk_mul_f32 v[138:139], v[138:139], s[36:37] op_sel_hi:[1,0]
	v_pk_mul_f32 v[140:141], v[140:141], s[36:37] op_sel_hi:[1,0]
	v_pk_mul_f32 v[142:143], v[142:143], s[36:37] op_sel_hi:[1,0]
	v_med3_f32 v80, v80, s40, v216
	v_med3_f32 v81, v81, s40, v216
	v_med3_f32 v82, v82, s40, v216
	v_med3_f32 v83, v83, s40, v216
	v_med3_f32 v84, v84, s40, v216
	v_med3_f32 v85, v85, s40, v216
	v_med3_f32 v86, v86, s40, v216
	v_med3_f32 v87, v87, s40, v216
	v_med3_f32 v88, v88, s40, v216
	v_med3_f32 v89, v89, s40, v216
	v_med3_f32 v90, v90, s40, v216
	v_med3_f32 v91, v91, s40, v216
	v_med3_f32 v92, v92, s40, v216
	v_med3_f32 v93, v93, s40, v216
	v_med3_f32 v94, v94, s40, v216
	v_med3_f32 v95, v95, s40, v216
	v_med3_f32 v96, v96, s40, v216
	v_med3_f32 v97, v97, s40, v216
	v_med3_f32 v98, v98, s40, v216
	v_med3_f32 v99, v99, s40, v216
	v_med3_f32 v100, v100, s40, v216
	v_med3_f32 v101, v101, s40, v216
	v_med3_f32 v102, v102, s40, v216
	v_med3_f32 v103, v103, s40, v216
	v_med3_f32 v104, v104, s40, v216
	v_med3_f32 v105, v105, s40, v216
	v_med3_f32 v106, v106, s40, v216
	v_med3_f32 v107, v107, s40, v216
	v_med3_f32 v108, v108, s40, v216
	v_med3_f32 v109, v109, s40, v216
	v_med3_f32 v110, v110, s40, v216
	v_med3_f32 v111, v111, s40, v216
	v_med3_f32 v112, v112, s40, v216
	v_med3_f32 v113, v113, s40, v216
	v_med3_f32 v114, v114, s40, v216
	v_med3_f32 v115, v115, s40, v216
	v_med3_f32 v116, v116, s40, v216
	v_med3_f32 v117, v117, s40, v216
	v_med3_f32 v118, v118, s40, v216
	v_med3_f32 v119, v119, s40, v216
	v_med3_f32 v120, v120, s40, v216
	v_med3_f32 v121, v121, s40, v216
	v_med3_f32 v122, v122, s40, v216
	v_med3_f32 v123, v123, s40, v216
	v_med3_f32 v124, v124, s40, v216
	v_med3_f32 v125, v125, s40, v216
	v_med3_f32 v126, v126, s40, v216
	v_med3_f32 v127, v127, s40, v216
	v_med3_f32 v128, v128, s40, v216
	v_med3_f32 v129, v129, s40, v216
	v_med3_f32 v130, v130, s40, v216
	v_med3_f32 v131, v131, s40, v216
	v_med3_f32 v132, v132, s40, v216
	v_med3_f32 v133, v133, s40, v216
	v_med3_f32 v134, v134, s40, v216
	v_med3_f32 v135, v135, s40, v216
	v_med3_f32 v136, v136, s40, v216
	v_med3_f32 v137, v137, s40, v216
	v_med3_f32 v138, v138, s40, v216
	v_med3_f32 v139, v139, s40, v216
	v_med3_f32 v140, v140, s40, v216
	v_med3_f32 v141, v141, s40, v216
	v_med3_f32 v142, v142, s40, v216
	v_med3_f32 v143, v143, s40, v216
	v_pk_add_f32 v[80:81], v[80:81], s[38:39] op_sel_hi:[1,0]
	v_pk_add_f32 v[82:83], v[82:83], s[38:39] op_sel_hi:[1,0]
	v_pk_add_f32 v[84:85], v[84:85], s[38:39] op_sel_hi:[1,0]
	v_pk_add_f32 v[86:87], v[86:87], s[38:39] op_sel_hi:[1,0]
	v_pk_add_f32 v[88:89], v[88:89], s[38:39] op_sel_hi:[1,0]
	v_pk_add_f32 v[90:91], v[90:91], s[38:39] op_sel_hi:[1,0]
	v_pk_add_f32 v[92:93], v[92:93], s[38:39] op_sel_hi:[1,0]
	v_pk_add_f32 v[94:95], v[94:95], s[38:39] op_sel_hi:[1,0]
	v_pk_add_f32 v[96:97], v[96:97], s[38:39] op_sel_hi:[1,0]
	v_pk_add_f32 v[98:99], v[98:99], s[38:39] op_sel_hi:[1,0]
	v_pk_add_f32 v[100:101], v[100:101], s[38:39] op_sel_hi:[1,0]
	v_pk_add_f32 v[102:103], v[102:103], s[38:39] op_sel_hi:[1,0]
	v_pk_add_f32 v[104:105], v[104:105], s[38:39] op_sel_hi:[1,0]
	v_pk_add_f32 v[106:107], v[106:107], s[38:39] op_sel_hi:[1,0]
	v_pk_add_f32 v[108:109], v[108:109], s[38:39] op_sel_hi:[1,0]
	v_pk_add_f32 v[110:111], v[110:111], s[38:39] op_sel_hi:[1,0]
	v_pk_add_f32 v[112:113], v[112:113], s[38:39] op_sel_hi:[1,0]
	v_pk_add_f32 v[114:115], v[114:115], s[38:39] op_sel_hi:[1,0]
	v_pk_add_f32 v[116:117], v[116:117], s[38:39] op_sel_hi:[1,0]
	v_pk_add_f32 v[118:119], v[118:119], s[38:39] op_sel_hi:[1,0]
	v_pk_add_f32 v[120:121], v[120:121], s[38:39] op_sel_hi:[1,0]
; #define LAS __attribute__((address_space(3)))
; __device__ __forceinline__ unsigned pk4_f8(float a, float b, float c, float d) { int w = __builtin_amdgcn_cvt_pk_fp8_f32(a, b, 0, false); w = __builtin_amdgcn_cvt_pk_fp8_f32(c, d, w, true); return (unsigned)w; }
; #define LDS_WAIT() asm volatile("s_waitcnt lgkmcnt(0)" ::: "memory")
;     ...
;         int dr0 = n0; if (MAP == 1) { if (n0 < DFF) dr0 = (n0 >> 7) * 256 + (n0 & 127); else { const int uo = n0 - DFF; dr0 = (uo >> 7) * 256 + 128 + (uo & 127); } }
; #pragma unroll 8
;         for (int i = 0; i < 32; ++i) { const int kk = 2 * i + (lane >> 5); scr[kk * 33 + (lane & 31)] = W[(size_t)(k0 + kk) * ldw + n0 + (lane & 31)]; }
;         LDS_WAIT(); asm volatile("" ::: "memory");
;         const int c = lane & 3;
; #pragma unroll
;         for (int j = 0; j < 2; ++j) { const int n = (lane >> 2) + 16 * j; const LAS float* sp = scr + (16 * c) * 33 + n;
;             u32x4 o;
;             if (QI8) { o.x = pk4_i8(sp[0 * 33], sp[1 * 33], sp[2 * 33], sp[3 * 33], scl); o.y = pk4_i8(sp[4 * 33], sp[5 * 33], sp[6 * 33], sp[7 * 33], scl);
;                 o.z = pk4_i8(sp[8 * 33], sp[9 * 33], sp[10 * 33], sp[11 * 33], scl); o.w = pk4_i8(sp[12 * 33], sp[13 * 33], sp[14 * 33], sp[15 * 33], scl); }
;             else {
;             o.x = pk4_f8(sp[0 * 33] * scl, sp[1 * 33] * scl, sp[2 * 33] * scl, sp[3 * 33] * scl); o.y = pk4_f8(sp[4 * 33] * scl, sp[5 * 33] * scl, sp[6 * 33] * scl, sp[7 * 33] * scl);
;             o.z = pk4_f8(sp[8 * 33] * scl, sp[9 * 33] * scl, sp[10 * 33] * scl, sp[11 * 33] * scl); o.w = pk4_f8(sp[12 * 33] * scl, sp[13 * 33] * scl, sp[14 * 33] * scl, sp[15 * 33] * scl); }
;             *(u32x4*)(WT + (size_t)(dr0 + n) * K + k0 + 16 * c) = o; }
	v_pk_add_f32 v[122:123], v[122:123], s[38:39] op_sel_hi:[1,0]
	v_pk_add_f32 v[124:125], v[124:125], s[38:39] op_sel_hi:[1,0]
	v_pk_add_f32 v[126:127], v[126:127], s[38:39] op_sel_hi:[1,0]
	v_pk_add_f32 v[128:129], v[128:129], s[38:39] op_sel_hi:[1,0]
	v_pk_add_f32 v[130:131], v[130:131], s[38:39] op_sel_hi:[1,0]
	v_pk_add_f32 v[132:133], v[132:133], s[38:39] op_sel_hi:[1,0]
	v_pk_add_f32 v[134:135], v[134:135], s[38:39] op_sel_hi:[1,0]
	v_pk_add_f32 v[136:137], v[136:137], s[38:39] op_sel_hi:[1,0]
	v_pk_add_f32 v[138:139], v[138:139], s[38:39] op_sel_hi:[1,0]
	v_pk_add_f32 v[140:141], v[140:141], s[38:39] op_sel_hi:[1,0]
	v_pk_add_f32 v[142:143], v[142:143], s[38:39] op_sel_hi:[1,0]
	v_perm_b32 v204, v84, v80, s41
	v_perm_b32 v205, v92, v88, s41
	v_perm_b32 v184, v205, v204, s42
	v_perm_b32 v204, v100, v96, s41
	v_perm_b32 v205, v108, v104, s41
	v_perm_b32 v185, v205, v204, s42
	v_perm_b32 v204, v116, v112, s41
	v_perm_b32 v205, v124, v120, s41
	v_perm_b32 v186, v205, v204, s42
	v_perm_b32 v204, v132, v128, s41
	v_perm_b32 v205, v140, v136, s41
	v_perm_b32 v187, v205, v204, s42
	v_perm_b32 v204, v85, v81, s41
	v_perm_b32 v205, v93, v89, s41
	v_perm_b32 v188, v205, v204, s42
	v_perm_b32 v204, v101, v97, s41
	v_perm_b32 v205, v109, v105, s41
	v_perm_b32 v189, v205, v204, s42
	v_perm_b32 v204, v117, v113, s41
	v_perm_b32 v205, v125, v121, s41
	v_perm_b32 v190, v205, v204, s42
	v_perm_b32 v204, v133, v129, s41
	v_perm_b32 v205, v141, v137, s41
	v_perm_b32 v191, v205, v204, s42
	v_perm_b32 v204, v86, v82, s41
	v_perm_b32 v205, v94, v90, s41
	v_perm_b32 v192, v205, v204, s42
	v_perm_b32 v204, v102, v98, s41
	v_perm_b32 v205, v110, v106, s41
	v_perm_b32 v193, v205, v204, s42
	v_perm_b32 v204, v118, v114, s41
	v_perm_b32 v205, v126, v122, s41
	v_perm_b32 v194, v205, v204, s42
	v_perm_b32 v204, v134, v130, s41
	v_perm_b32 v205, v142, v138, s41
	v_perm_b32 v195, v205, v204, s42
	v_perm_b32 v204, v87, v83, s41
	v_perm_b32 v205, v95, v91, s41
	v_perm_b32 v196, v205, v204, s42
	v_perm_b32 v204, v103, v99, s41
	v_perm_b32 v205, v111, v107, s41
	v_perm_b32 v197, v205, v204, s42
	v_perm_b32 v204, v119, v115, s41
	v_perm_b32 v205, v127, v123, s41
	v_perm_b32 v198, v205, v204, s42
	v_perm_b32 v204, v135, v131, s41
	v_perm_b32 v205, v143, v139, s41
	v_perm_b32 v199, v205, v204, s42
	ds_write_b128 v213, v[184:187] offset:0
	ds_write_b128 v213, v[188:191] offset:144
	ds_write_b128 v213, v[192:195] offset:288
	ds_write_b128 v213, v[196:199] offset:432
	s_lshl_b32 s26, s61, 1
	s_add_i32 s27, s26, 0xffffaa80
	s_cmp_lt_u32 s61, 0x2b00
	s_cselect_b32 s26, s26, s27
	s_add_i32 s26, s26, s17
	s_mul_i32 s26, s26, 0x1000
	s_add_u32 s26, s26, s60
	s_add_u32 s54, s44, s26
	s_addc_u32 s55, s45, 0
	s_waitcnt lgkmcnt(0)
	s_barrier
	ds_read_b128 v[184:187], v214 offset:0
	ds_read_b128 v[188:191], v214 offset:1152
	ds_read_b128 v[192:195], v214 offset:2304
	ds_read_b128 v[196:199], v214 offset:3456
	s_waitcnt lgkmcnt(3)
	global_store_dwordx4 v215, v[184:187], s[54:55]
	s_add_u32 s54, s54, 0x8000
	s_addc_u32 s55, s55, 0
	s_waitcnt lgkmcnt(2)
	global_store_dwordx4 v215, v[188:191], s[54:55]
	s_add_u32 s54, s54, 0x8000
	s_addc_u32 s55, s55, 0
	s_waitcnt lgkmcnt(1)
	global_store_dwordx4 v215, v[192:195], s[54:55]
	s_add_u32 s54, s54, 0x8000
	s_addc_u32 s55, s55, 0
	s_waitcnt lgkmcnt(0)
	global_store_dwordx4 v215, v[196:199], s[54:55]
	s_mov_b32 s19, s59
	s_cmp_lt_u32 s19, 0xac0
	s_cbranch_scc0 .Lf8t_f1in0_end
	s_add_i32 s59, s19, s96
	s_cmp_lt_u32 s59, 0xac0
	s_cbranch_scc0 .Lf8t_f1in0_b_nonext
	s_mul_hi_u32 s20, s59, 0x2fa0be9
	s_mul_i32 s21, s20, 86
	s_sub_i32 s21, s59, s21
	s_lshl_b32 s60, s20, 7
	s_lshl_b32 s61, s21, 8
	s_add_i32 s24, s60, s16
	s_mul_i32 s24, s24, 0x15800
	s_lshl_b32 s25, s61, 2
	s_add_u32 s24, s24, s25
	s_add_u32 s52, s50, s24
	s_addc_u32 s53, s51, 0
	global_load_dwordx4 v[80:83], v212, s[52:53] nt
	s_add_u32 s52, s52, 0x15800
	s_addc_u32 s53, s53, 0
	global_load_dwordx4 v[84:87], v212, s[52:53] nt
	s_add_u32 s52, s52, 0x15800
	s_addc_u32 s53, s53, 0
	global_load_dwordx4 v[88:91], v212, s[52:53] nt
	s_add_u32 s52, s52, 0x15800
	s_addc_u32 s53, s53, 0
	global_load_dwordx4 v[92:95], v212, s[52:53] nt
	s_add_u32 s52, s52, 0x15800
	s_addc_u32 s53, s53, 0
	global_load_dwordx4 v[96:99], v212, s[52:53] nt
	s_add_u32 s52, s52, 0x15800
	s_addc_u32 s53, s53, 0
	global_load_dwordx4 v[100:103], v212, s[52:53] nt
	s_add_u32 s52, s52, 0x15800
	s_addc_u32 s53, s53, 0
	global_load_dwordx4 v[104:107], v212, s[52:53] nt
	s_add_u32 s52, s52, 0x15800
	s_addc_u32 s53, s53, 0
	global_load_dwordx4 v[108:111], v212, s[52:53] nt
	s_add_u32 s52, s52, 0x15800
	s_addc_u32 s53, s53, 0
	global_load_dwordx4 v[112:115], v212, s[52:53] nt
	s_add_u32 s52, s52, 0x15800
	s_addc_u32 s53, s53, 0
	global_load_dwordx4 v[116:119], v212, s[52:53] nt
	s_add_u32 s52, s52, 0x15800
	s_addc_u32 s53, s53, 0
	global_load_dwordx4 v[120:123], v212, s[52:53] nt
	s_add_u32 s52, s52, 0x15800
	s_addc_u32 s53, s53, 0
	global_load_dwordx4 v[124:127], v212, s[52:53] nt
	s_add_u32 s52, s52, 0x15800
	s_addc_u32 s53, s53, 0
	global_load_dwordx4 v[128:131], v212, s[52:53] nt
	s_add_u32 s52, s52, 0x15800
	s_addc_u32 s53, s53, 0
	global_load_dwordx4 v[132:135], v212, s[52:53] nt
	s_add_u32 s52, s52, 0x15800
	s_addc_u32 s53, s53, 0
	global_load_dwordx4 v[136:139], v212, s[52:53] nt
	s_add_u32 s52, s52, 0x15800
	s_addc_u32 s53, s53, 0
	global_load_dwordx4 v[140:143], v212, s[52:53] nt
	s_waitcnt vmcnt(20)
	s_branch .Lf8t_f1in0_b_go

; #define LAS __attribute__((address_space(3)))
;     if (ldw == 0) ldw = N;
;     LAS float* scr = (LAS float*)(F.lds + F.wave * 16384); const int lane = F.lane;
;     const int nblk = N / 32, nitems = (K / 64) * nblk;
;     for (int item = F.gw; item < nitems; item += F.NGW) { const int kb = item / nblk, nb = item % nblk, k0 = 64 * kb, n0 = 32 * nb;
;         int dr0 = n0; if (MAP == 1) { if (n0 < DFF) dr0 = (n0 >> 7) * 256 + (n0 & 127); else { const int uo = n0 - DFF; dr0 = (uo >> 7) * 256 + 128 + (uo & 127); } }
; #pragma unroll 8
;         for (int i = 0; i < 32; ++i) { const int kk = 2 * i + (lane >> 5); scr[kk * 33 + (lane & 31)] = W[(size_t)(k0 + kk) * ldw + n0 + (lane & 31)]; }
.LBB0_22:
.LBB0_23:
	s_barrier
	s_load_dwordx2 s[50:51], s[74:75], 0x40
	v_readlane_b32 s16, v240, 2
	v_lshlrev_b32_e32 v212, 4, v178
	v_mov_b32_e32 v216, 0x42fe0000
	s_mov_b32 s36, 0x43000000
	s_mov_b32 s37, 0
	s_mov_b32 s38, 0x4b400000
	s_mov_b32 s39, 0
	s_mov_b32 s40, 0xc2fe0000
	s_mov_b32 s41, 0x0c0c0400
	s_mov_b32 s42, 0x05040100
	s_lshl_b32 s17, s16, 5
	v_mul_u32_u24_e32 v213, 0x240, v178
	s_lshl_b32 s18, s16, 4
	v_add_u32_e32 v213, s18, v213
	v_lshrrev_b32_e32 v204, 3, v178
	v_and_b32_e32 v205, 7, v178
	s_lshl_b32 s18, s16, 5
	v_add_u32_e32 v206, s18, v204
	v_mul_u32_u24_e32 v214, 0x90, v206
	v_lshl_add_u32 v214, v205, 4, v214
	v_mul_u32_u24_e32 v215, 0x2b00, v204
	v_lshl_add_u32 v215, v205, 4, v215
	s_lshl_b32 s16, s16, 4
	s_waitcnt lgkmcnt(0)
	s_add_u32 s44, s90, 0x12f00000
	s_addc_u32 s45, s91, 0
	s_mov_b32 s19, s2
	s_cmp_lt_u32 s19, 0x560
	s_cbranch_scc0 .Lf8t_f1dn0_end
	s_mul_hi_u32 s20, s19, 0x10000000
	s_mul_i32 s21, s20, 16
	s_sub_i32 s21, s19, s21
	s_lshl_b32 s60, s20, 7
	s_lshl_b32 s61, s21, 8
	s_add_i32 s24, s60, s16
	s_mul_i32 s24, s24, 0x4000
	s_lshl_b32 s25, s61, 2
	s_add_u32 s24, s24, s25
	s_add_u32 s52, s50, s24
	s_addc_u32 s53, s51, 0
	global_load_dwordx4 v[80:83], v212, s[52:53] nt
	s_add_u32 s52, s52, 0x4000
	s_addc_u32 s53, s53, 0
	global_load_dwordx4 v[84:87], v212, s[52:53] nt
	s_add_u32 s52, s52, 0x4000
	s_addc_u32 s53, s53, 0
	global_load_dwordx4 v[88:91], v212, s[52:53] nt
	s_add_u32 s52, s52, 0x4000
	s_addc_u32 s53, s53, 0
	global_load_dwordx4 v[92:95], v212, s[52:53] nt
	s_add_u32 s52, s52, 0x4000
	s_addc_u32 s53, s53, 0
	global_load_dwordx4 v[96:99], v212, s[52:53] nt
	s_add_u32 s52, s52, 0x4000
	s_addc_u32 s53, s53, 0
	global_load_dwordx4 v[100:103], v212, s[52:53] nt
	s_add_u32 s52, s52, 0x4000
	s_addc_u32 s53, s53, 0
	global_load_dwordx4 v[104:107], v212, s[52:53] nt
	s_add_u32 s52, s52, 0x4000
	s_addc_u32 s53, s53, 0
	global_load_dwordx4 v[108:111], v212, s[52:53] nt
	s_add_u32 s52, s52, 0x4000
	s_addc_u32 s53, s53, 0
	global_load_dwordx4 v[112:115], v212, s[52:53] nt
	s_add_u32 s52, s52, 0x4000
	s_addc_u32 s53, s53, 0
	global_load_dwordx4 v[116:119], v212, s[52:53] nt
	s_add_u32 s52, s52, 0x4000
	s_addc_u32 s53, s53, 0
	global_load_dwordx4 v[120:123], v212, s[52:53] nt
	s_add_u32 s52, s52, 0x4000
	s_addc_u32 s53, s53, 0
	global_load_dwordx4 v[124:127], v212, s[52:53] nt
	s_add_u32 s52, s52, 0x4000
	s_addc_u32 s53, s53, 0
	global_load_dwordx4 v[128:131], v212, s[52:53] nt
	s_add_u32 s52, s52, 0x4000
	s_addc_u32 s53, s53, 0
	global_load_dwordx4 v[132:135], v212, s[52:53] nt
	s_add_u32 s52, s52, 0x4000
	s_addc_u32 s53, s53, 0
	global_load_dwordx4 v[136:139], v212, s[52:53] nt
	s_add_u32 s52, s52, 0x4000
	s_addc_u32 s53, s53, 0
	global_load_dwordx4 v[140:143], v212, s[52:53] nt
	s_mov_b32 s58, 1
.Lf8t_f1dn0_loop:
	s_add_i32 s59, s19, s96
	s_cmp_lt_u32 s59, 0x560
	s_cbranch_scc0 .Lf8t_f1dn0_a_nonext
	s_mul_hi_u32 s20, s59, 0x10000000
	s_mul_i32 s21, s20, 16
	s_sub_i32 s21, s59, s21
	s_lshl_b32 s62, s20, 7
	s_lshl_b32 s63, s21, 8
	s_add_i32 s24, s62, s16
	s_mul_i32 s24, s24, 0x4000
	s_lshl_b32 s25, s63, 2
	s_add_u32 s24, s24, s25
	s_add_u32 s52, s50, s24
	s_addc_u32 s53, s51, 0
	global_load_dwordx4 v[16:19], v212, s[52:53] nt
	s_add_u32 s52, s52, 0x4000
	s_addc_u32 s53, s53, 0
	global_load_dwordx4 v[20:23], v212, s[52:53] nt
	s_add_u32 s52, s52, 0x4000
	s_addc_u32 s53, s53, 0
	global_load_dwordx4 v[24:27], v212, s[52:53] nt
	s_add_u32 s52, s52, 0x4000
	s_addc_u32 s53, s53, 0
	global_load_dwordx4 v[28:31], v212, s[52:53] nt
	s_add_u32 s52, s52, 0x4000
	s_addc_u32 s53, s53, 0
	global_load_dwordx4 v[32:35], v212, s[52:53] nt
	s_add_u32 s52, s52, 0x4000
	s_addc_u32 s53, s53, 0
	global_load_dwordx4 v[36:39], v212, s[52:53] nt
	s_add_u32 s52, s52, 0x4000
	s_addc_u32 s53, s53, 0
	global_load_dwordx4 v[40:43], v212, s[52:53] nt
	s_add_u32 s52, s52, 0x4000
	s_addc_u32 s53, s53, 0
	global_load_dwordx4 v[44:47], v212, s[52:53] nt
	s_add_u32 s52, s52, 0x4000
	s_addc_u32 s53, s53, 0
	global_load_dwordx4 v[48:51], v212, s[52:53] nt
	s_add_u32 s52, s52, 0x4000
	s_addc_u32 s53, s53, 0
	global_load_dwordx4 v[52:55], v212, s[52:53] nt
	s_add_u32 s52, s52, 0x4000
	s_addc_u32 s53, s53, 0
	global_load_dwordx4 v[56:59], v212, s[52:53] nt
	s_add_u32 s52, s52, 0x4000
	s_addc_u32 s53, s53, 0
	global_load_dwordx4 v[60:63], v212, s[52:53] nt
	s_add_u32 s52, s52, 0x4000
	s_addc_u32 s53, s53, 0
	global_load_dwordx4 v[64:67], v212, s[52:53] nt
	s_add_u32 s52, s52, 0x4000
	s_addc_u32 s53, s53, 0
	global_load_dwordx4 v[68:71], v212, s[52:53] nt
	s_add_u32 s52, s52, 0x4000
	s_addc_u32 s53, s53, 0
	global_load_dwordx4 v[144:147], v212, s[52:53] nt
	s_add_u32 s52, s52, 0x4000
	s_addc_u32 s53, s53, 0
	global_load_dwordx4 v[148:151], v212, s[52:53] nt
	s_cmp_eq_u32 s58, 1
	s_cbranch_scc1 .Lf8t_f1dn0_a_first
	s_waitcnt vmcnt(20)
	s_branch .Lf8t_f1dn0_a_go

; __device__ __forceinline__ unsigned pk4_f8(float a, float b, float c, float d) { int w = __builtin_amdgcn_cvt_pk_fp8_f32(a, b, 0, false); w = __builtin_amdgcn_cvt_pk_fp8_f32(c, d, w, true); return (unsigned)w; }
;     ...
;             else {
;             o.x = pk4_f8(sp[0 * 33] * scl, sp[1 * 33] * scl, sp[2 * 33] * scl, sp[3 * 33] * scl); o.y = pk4_f8(sp[4 * 33] * scl, sp[5 * 33] * scl, sp[6 * 33] * scl, sp[7 * 33] * scl);
;             o.z = pk4_f8(sp[8 * 33] * scl, sp[9 * 33] * scl, sp[10 * 33] * scl, sp[11 * 33] * scl); o.w = pk4_f8(sp[12 * 33] * scl, sp[13 * 33] * scl, sp[14 * 33] * scl, sp[15 * 33] * scl); }
;             *(u32x4*)(WT + (size_t)(dr0 + n) * K + k0 + 16 * c) = o; }
.Lf8t_f1dn0_a_go:
	s_mov_b32 s58, 0
	v_pk_mul_f32 v[80:81], v[80:81], s[36:37] op_sel_hi:[1,0]
	v_pk_mul_f32 v[82:83], v[82:83], s[36:37] op_sel_hi:[1,0]
	v_pk_mul_f32 v[84:85], v[84:85], s[36:37] op_sel_hi:[1,0]
	v_pk_mul_f32 v[86:87], v[86:87], s[36:37] op_sel_hi:[1,0]
	v_pk_mul_f32 v[88:89], v[88:89], s[36:37] op_sel_hi:[1,0]
	v_pk_mul_f32 v[90:91], v[90:91], s[36:37] op_sel_hi:[1,0]
	v_pk_mul_f32 v[92:93], v[92:93], s[36:37] op_sel_hi:[1,0]
	v_pk_mul_f32 v[94:95], v[94:95], s[36:37] op_sel_hi:[1,0]
	v_pk_mul_f32 v[96:97], v[96:97], s[36:37] op_sel_hi:[1,0]
	v_pk_mul_f32 v[98:99], v[98:99], s[36:37] op_sel_hi:[1,0]
	v_pk_mul_f32 v[100:101], v[100:101], s[36:37] op_sel_hi:[1,0]
	v_pk_mul_f32 v[102:103], v[102:103], s[36:37] op_sel_hi:[1,0]
	v_pk_mul_f32 v[104:105], v[104:105], s[36:37] op_sel_hi:[1,0]
	v_pk_mul_f32 v[106:107], v[106:107], s[36:37] op_sel_hi:[1,0]
	v_pk_mul_f32 v[108:109], v[108:109], s[36:37] op_sel_hi:[1,0]
	v_pk_mul_f32 v[110:111], v[110:111], s[36:37] op_sel_hi:[1,0]
	v_pk_mul_f32 v[112:113], v[112:113], s[36:37] op_sel_hi:[1,0]
	v_pk_mul_f32 v[114:115], v[114:115], s[36:37] op_sel_hi:[1,0]
	v_pk_mul_f32 v[116:117], v[116:117], s[36:37] op_sel_hi:[1,0]
	v_pk_mul_f32 v[118:119], v[118:119], s[36:37] op_sel_hi:[1,0]
	v_pk_mul_f32 v[120:121], v[120:121], s[36:37] op_sel_hi:[1,0]
	v_pk_mul_f32 v[122:123], v[122:123], s[36:37] op_sel_hi:[1,0]
	v_pk_mul_f32 v[124:125], v[124:125], s[36:37] op_sel_hi:[1,0]
	v_pk_mul_f32 v[126:127], v[126:127], s[36:37] op_sel_hi:[1,0]
	v_pk_mul_f32 v[128:129], v[128:129], s[36:37] op_sel_hi:[1,0]
	v_pk_mul_f32 v[130:131], v[130:131], s[36:37] op_sel_hi:[1,0]
	v_pk_mul_f32 v[132:133], v[132:133], s[36:37] op_sel_hi:[1,0]
	v_pk_mul_f32 v[134:135], v[134:135], s[36:37] op_sel_hi:[1,0]
	v_pk_mul_f32 v[136:137], v[136:137], s[36:37] op_sel_hi:[1,0]
	v_pk_mul_f32 v[138:139], v[138:139], s[36:37] op_sel_hi:[1,0]
	v_pk_mul_f32 v[140:141], v[140:141], s[36:37] op_sel_hi:[1,0]
	v_pk_mul_f32 v[142:143], v[142:143], s[36:37] op_sel_hi:[1,0]
	v_cvt_pk_fp8_f32 v184, v80, v84
	v_cvt_pk_fp8_f32 v184, v88, v92 op_sel:[0,0,1]
	v_cvt_pk_fp8_f32 v185, v96, v100
	v_cvt_pk_fp8_f32 v185, v104, v108 op_sel:[0,0,1]
	v_cvt_pk_fp8_f32 v186, v112, v116
	v_cvt_pk_fp8_f32 v186, v120, v124 op_sel:[0,0,1]
	v_cvt_pk_fp8_f32 v187, v128, v132
	v_cvt_pk_fp8_f32 v187, v136, v140 op_sel:[0,0,1]
	v_cvt_pk_fp8_f32 v188, v81, v85
	v_cvt_pk_fp8_f32 v188, v89, v93 op_sel:[0,0,1]
	v_cvt_pk_fp8_f32 v189, v97, v101
	v_cvt_pk_fp8_f32 v189, v105, v109 op_sel:[0,0,1]
	v_cvt_pk_fp8_f32 v190, v113, v117
	v_cvt_pk_fp8_f32 v190, v121, v125 op_sel:[0,0,1]
	v_cvt_pk_fp8_f32 v191, v129, v133
	v_cvt_pk_fp8_f32 v191, v137, v141 op_sel:[0,0,1]
	v_cvt_pk_fp8_f32 v192, v82, v86
	v_cvt_pk_fp8_f32 v192, v90, v94 op_sel:[0,0,1]
	v_cvt_pk_fp8_f32 v193, v98, v102
	v_cvt_pk_fp8_f32 v193, v106, v110 op_sel:[0,0,1]
	v_cvt_pk_fp8_f32 v194, v114, v118
	v_cvt_pk_fp8_f32 v194, v122, v126 op_sel:[0,0,1]
	v_cvt_pk_fp8_f32 v195, v130, v134
	v_cvt_pk_fp8_f32 v195, v138, v142 op_sel:[0,0,1]
	v_cvt_pk_fp8_f32 v196, v83, v87
	v_cvt_pk_fp8_f32 v196, v91, v95 op_sel:[0,0,1]
	v_cvt_pk_fp8_f32 v197, v99, v103
	v_cvt_pk_fp8_f32 v197, v107, v111 op_sel:[0,0,1]
	v_cvt_pk_fp8_f32 v198, v115, v119
	v_cvt_pk_fp8_f32 v198, v123, v127 op_sel:[0,0,1]
	v_cvt_pk_fp8_f32 v199, v131, v135
	v_cvt_pk_fp8_f32 v199, v139, v143 op_sel:[0,0,1]
	ds_write_b128 v213, v[184:187] offset:0
	ds_write_b128 v213, v[188:191] offset:144
	ds_write_b128 v213, v[192:195] offset:288
	ds_write_b128 v213, v[196:199] offset:432
	s_mov_b32 s26, s61
	s_add_i32 s26, s26, s17
	s_mul_i32 s26, s26, 0x2b00
	s_add_u32 s26, s26, s60
	s_add_u32 s54, s44, s26
	s_addc_u32 s55, s45, 0
	s_waitcnt lgkmcnt(0)
	s_barrier
	ds_read_b128 v[184:187], v214 offset:0
	ds_read_b128 v[188:191], v214 offset:1152
	ds_read_b128 v[192:195], v214 offset:2304
	ds_read_b128 v[196:199], v214 offset:3456
	s_waitcnt lgkmcnt(3)
	global_store_dwordx4 v215, v[184:187], s[54:55]
	s_add_u32 s54, s54, 0x15800
	s_addc_u32 s55, s55, 0
	s_waitcnt lgkmcnt(2)
	global_store_dwordx4 v215, v[188:191], s[54:55]
	s_add_u32 s54, s54, 0x15800
	s_addc_u32 s55, s55, 0
	s_waitcnt lgkmcnt(1)
	global_store_dwordx4 v215, v[192:195], s[54:55]
	s_add_u32 s54, s54, 0x15800
	s_addc_u32 s55, s55, 0
	s_waitcnt lgkmcnt(0)
	global_store_dwordx4 v215, v[196:199], s[54:55]
	s_mov_b32 s19, s59
	s_cmp_lt_u32 s19, 0x560
	s_cbranch_scc0 .Lf8t_f1dn0_end
	s_add_i32 s59, s19, s96
	s_cmp_lt_u32 s59, 0x560
	s_cbranch_scc0 .Lf8t_f1dn0_b_nonext
	s_mul_hi_u32 s20, s59, 0x10000000
	s_mul_i32 s21, s20, 16
	s_sub_i32 s21, s59, s21
	s_lshl_b32 s60, s20, 7
	s_lshl_b32 s61, s21, 8
	s_add_i32 s24, s60, s16
	s_mul_i32 s24, s24, 0x4000
	s_lshl_b32 s25, s61, 2
	s_add_u32 s24, s24, s25
	s_add_u32 s52, s50, s24
	s_addc_u32 s53, s51, 0
	global_load_dwordx4 v[80:83], v212, s[52:53] nt
	s_add_u32 s52, s52, 0x4000
	s_addc_u32 s53, s53, 0
	global_load_dwordx4 v[84:87], v212, s[52:53] nt
	s_add_u32 s52, s52, 0x4000
	s_addc_u32 s53, s53, 0
	global_load_dwordx4 v[88:91], v212, s[52:53] nt
	s_add_u32 s52, s52, 0x4000
	s_addc_u32 s53, s53, 0
	global_load_dwordx4 v[92:95], v212, s[52:53] nt
	s_add_u32 s52, s52, 0x4000
	s_addc_u32 s53, s53, 0
	global_load_dwordx4 v[96:99], v212, s[52:53] nt
	s_add_u32 s52, s52, 0x4000
	s_addc_u32 s53, s53, 0
	global_load_dwordx4 v[100:103], v212, s[52:53] nt
	s_add_u32 s52, s52, 0x4000
	s_addc_u32 s53, s53, 0
	global_load_dwordx4 v[104:107], v212, s[52:53] nt
	s_add_u32 s52, s52, 0x4000
	s_addc_u32 s53, s53, 0
	global_load_dwordx4 v[108:111], v212, s[52:53] nt
	s_add_u32 s52, s52, 0x4000
	s_addc_u32 s53, s53, 0
	global_load_dwordx4 v[112:115], v212, s[52:53] nt
	s_add_u32 s52, s52, 0x4000
	s_addc_u32 s53, s53, 0
	global_load_dwordx4 v[116:119], v212, s[52:53] nt
	s_add_u32 s52, s52, 0x4000
	s_addc_u32 s53, s53, 0
	global_load_dwordx4 v[120:123], v212, s[52:53] nt
	s_add_u32 s52, s52, 0x4000
	s_addc_u32 s53, s53, 0
	global_load_dwordx4 v[124:127], v212, s[52:53] nt
	s_add_u32 s52, s52, 0x4000
	s_addc_u32 s53, s53, 0
	global_load_dwordx4 v[128:131], v212, s[52:53] nt
	s_add_u32 s52, s52, 0x4000
	s_addc_u32 s53, s53, 0
	global_load_dwordx4 v[132:135], v212, s[52:53] nt
	s_add_u32 s52, s52, 0x4000
	s_addc_u32 s53, s53, 0
	global_load_dwordx4 v[136:139], v212, s[52:53] nt
	s_add_u32 s52, s52, 0x4000
	s_addc_u32 s53, s53, 0
	global_load_dwordx4 v[140:143], v212, s[52:53] nt
	s_waitcnt vmcnt(20)
	s_branch .Lf8t_f1dn0_b_go

; #define LAS __attribute__((address_space(3)))
;     if (ldw == 0) ldw = N;
;     LAS float* scr = (LAS float*)(F.lds + F.wave * 16384); const int lane = F.lane;
;     const int nblk = N / 32, nitems = (K / 64) * nblk;
;     for (int item = F.gw; item < nitems; item += F.NGW) { const int kb = item / nblk, nb = item % nblk, k0 = 64 * kb, n0 = 32 * nb;
;         int dr0 = n0; if (MAP == 1) { if (n0 < DFF) dr0 = (n0 >> 7) * 256 + (n0 & 127); else { const int uo = n0 - DFF; dr0 = (uo >> 7) * 256 + 128 + (uo & 127); } }
; #pragma unroll 8
;         for (int i = 0; i < 32; ++i) { const int kk = 2 * i + (lane >> 5); scr[kk * 33 + (lane & 31)] = W[(size_t)(k0 + kk) * ldw + n0 + (lane & 31)]; }
; __device__ __forceinline__ void p0_prologue(Frame& F) {
;     ...
;       transpose_f8_matrix<0, true>(F, W + 8192 + DRIN, D, 8192, w8, I8_W, ldw);
.LBB0_37:
	s_cmpk_gt_i32 s94, 0x3fff
	s_cbranch_scc1 .LBB0_42
	s_barrier
	s_load_dwordx2 s[50:51], s[74:75], 0x58
	v_readlane_b32 s16, v240, 2
	v_lshlrev_b32_e32 v212, 4, v178
	v_mov_b32_e32 v216, 0x42fe0000
	s_mov_b32 s36, 0x44fe0000
	s_mov_b32 s37, 0
	s_mov_b32 s38, 0x4b400000
	s_mov_b32 s39, 0
	s_mov_b32 s40, 0xc2fe0000
	s_mov_b32 s41, 0x0c0c0400
	s_mov_b32 s42, 0x05040100
	s_lshl_b32 s17, s16, 5
	v_mul_u32_u24_e32 v213, 0x240, v178
	s_lshl_b32 s18, s16, 4
	v_add_u32_e32 v213, s18, v213
	v_lshrrev_b32_e32 v204, 3, v178
	v_and_b32_e32 v205, 7, v178
	s_lshl_b32 s18, s16, 5
	v_add_u32_e32 v206, s18, v204
	v_mul_u32_u24_e32 v214, 0x90, v206
	v_lshl_add_u32 v214, v205, 4, v214
	v_mul_u32_u24_e32 v215, 0x1000, v204
	v_lshl_add_u32 v215, v205, 4, v215
	s_lshl_b32 s16, s16, 4
	s_waitcnt lgkmcnt(0)
	s_add_u32 s50, s50, 0xeb80
	s_addc_u32 s51, s51, 0
	s_add_u32 s44, s90, 0x35b00000
	s_addc_u32 s45, s91, 0
	s_mov_b32 s19, s2
	s_cmp_lt_u32 s19, 0x400
	s_cbranch_scc0 .Lf8t_win8a0_end
	s_mul_hi_u32 s20, s19, 0x8000000
	s_mul_i32 s21, s20, 32
	s_sub_i32 s21, s19, s21
	s_lshl_b32 s60, s20, 7
	s_lshl_b32 s61, s21, 8
	s_add_i32 s24, s60, s16
	s_mul_i32 s24, s24, 0x16b80
	s_lshl_b32 s25, s61, 2
	s_add_u32 s24, s24, s25
	s_add_u32 s52, s50, s24
	s_addc_u32 s53, s51, 0
	global_load_dwordx4 v[80:83], v212, s[52:53] nt
	s_add_u32 s52, s52, 0x16b80
	s_addc_u32 s53, s53, 0
	global_load_dwordx4 v[84:87], v212, s[52:53] nt
	s_add_u32 s52, s52, 0x16b80
	s_addc_u32 s53, s53, 0
	global_load_dwordx4 v[88:91], v212, s[52:53] nt
	s_add_u32 s52, s52, 0x16b80
	s_addc_u32 s53, s53, 0
	global_load_dwordx4 v[92:95], v212, s[52:53] nt
	s_add_u32 s52, s52, 0x16b80
	s_addc_u32 s53, s53, 0
	global_load_dwordx4 v[96:99], v212, s[52:53] nt
	s_add_u32 s52, s52, 0x16b80
	s_addc_u32 s53, s53, 0
	global_load_dwordx4 v[100:103], v212, s[52:53] nt
	s_add_u32 s52, s52, 0x16b80
	s_addc_u32 s53, s53, 0
	global_load_dwordx4 v[104:107], v212, s[52:53] nt
	s_add_u32 s52, s52, 0x16b80
	s_addc_u32 s53, s53, 0
	global_load_dwordx4 v[108:111], v212, s[52:53] nt
	s_add_u32 s52, s52, 0x16b80
	s_addc_u32 s53, s53, 0
	global_load_dwordx4 v[112:115], v212, s[52:53] nt
	s_add_u32 s52, s52, 0x16b80
	s_addc_u32 s53, s53, 0
	global_load_dwordx4 v[116:119], v212, s[52:53] nt
	s_add_u32 s52, s52, 0x16b80
	s_addc_u32 s53, s53, 0
	global_load_dwordx4 v[120:123], v212, s[52:53] nt
	s_add_u32 s52, s52, 0x16b80
	s_addc_u32 s53, s53, 0
	global_load_dwordx4 v[124:127], v212, s[52:53] nt
	s_add_u32 s52, s52, 0x16b80
	s_addc_u32 s53, s53, 0
	global_load_dwordx4 v[128:131], v212, s[52:53] nt
	s_add_u32 s52, s52, 0x16b80
	s_addc_u32 s53, s53, 0
	global_load_dwordx4 v[132:135], v212, s[52:53] nt
	s_add_u32 s52, s52, 0x16b80
	s_addc_u32 s53, s53, 0
	global_load_dwordx4 v[136:139], v212, s[52:53] nt
	s_add_u32 s52, s52, 0x16b80
	s_addc_u32 s53, s53, 0
	global_load_dwordx4 v[140:143], v212, s[52:53] nt
	s_mov_b32 s58, 1
.Lf8t_win8a0_loop:
	s_add_i32 s59, s19, s96
	s_cmp_lt_u32 s59, 0x400
	s_cbranch_scc0 .Lf8t_win8a0_a_nonext
	s_mul_hi_u32 s20, s59, 0x8000000
	s_mul_i32 s21, s20, 32
	s_sub_i32 s21, s59, s21
	s_lshl_b32 s62, s20, 7
	s_lshl_b32 s63, s21, 8
	s_add_i32 s24, s62, s16
	s_mul_i32 s24, s24, 0x16b80
	s_lshl_b32 s25, s63, 2
	s_add_u32 s24, s24, s25
	s_add_u32 s52, s50, s24
	s_addc_u32 s53, s51, 0
	global_load_dwordx4 v[16:19], v212, s[52:53] nt
	s_add_u32 s52, s52, 0x16b80
	s_addc_u32 s53, s53, 0
	global_load_dwordx4 v[20:23], v212, s[52:53] nt
	s_add_u32 s52, s52, 0x16b80
	s_addc_u32 s53, s53, 0
	global_load_dwordx4 v[24:27], v212, s[52:53] nt
	s_add_u32 s52, s52, 0x16b80
	s_addc_u32 s53, s53, 0
	global_load_dwordx4 v[28:31], v212, s[52:53] nt
	s_add_u32 s52, s52, 0x16b80
	s_addc_u32 s53, s53, 0
	global_load_dwordx4 v[32:35], v212, s[52:53] nt
	s_add_u32 s52, s52, 0x16b80
	s_addc_u32 s53, s53, 0
	global_load_dwordx4 v[36:39], v212, s[52:53] nt
	s_add_u32 s52, s52, 0x16b80
	s_addc_u32 s53, s53, 0
	global_load_dwordx4 v[40:43], v212, s[52:53] nt
	s_add_u32 s52, s52, 0x16b80
	s_addc_u32 s53, s53, 0
	global_load_dwordx4 v[44:47], v212, s[52:53] nt
	s_add_u32 s52, s52, 0x16b80
	s_addc_u32 s53, s53, 0
	global_load_dwordx4 v[48:51], v212, s[52:53] nt
	s_add_u32 s52, s52, 0x16b80
	s_addc_u32 s53, s53, 0
	global_load_dwordx4 v[52:55], v212, s[52:53] nt
	s_add_u32 s52, s52, 0x16b80
	s_addc_u32 s53, s53, 0
	global_load_dwordx4 v[56:59], v212, s[52:53] nt
	s_add_u32 s52, s52, 0x16b80
	s_addc_u32 s53, s53, 0
	global_load_dwordx4 v[60:63], v212, s[52:53] nt
	s_add_u32 s52, s52, 0x16b80
	s_addc_u32 s53, s53, 0
	global_load_dwordx4 v[64:67], v212, s[52:53] nt
	s_add_u32 s52, s52, 0x16b80
	s_addc_u32 s53, s53, 0
	global_load_dwordx4 v[68:71], v212, s[52:53] nt
	s_add_u32 s52, s52, 0x16b80
	s_addc_u32 s53, s53, 0
	global_load_dwordx4 v[144:147], v212, s[52:53] nt
	s_add_u32 s52, s52, 0x16b80
	s_addc_u32 s53, s53, 0
	global_load_dwordx4 v[148:151], v212, s[52:53] nt
	s_cmp_eq_u32 s58, 1
	s_cbranch_scc1 .Lf8t_win8a0_a_first
	s_waitcnt vmcnt(20)
	s_branch .Lf8t_win8a0_a_go

; __device__ __forceinline__ unsigned pk4_i8(float a, float b, float c, float d, float s) {
;     const unsigned ua = __float_as_uint(__builtin_amdgcn_fmed3f(a * s, -127.f, 127.f) + 12582912.f), ub = __float_as_uint(__builtin_amdgcn_fmed3f(b * s, -127.f, 127.f) + 12582912.f);
;     const unsigned uc = __float_as_uint(__builtin_amdgcn_fmed3f(c * s, -127.f, 127.f) + 12582912.f), ud = __float_as_uint(__builtin_amdgcn_fmed3f(d * s, -127.f, 127.f) + 12582912.f);
;     return (ua & 0xffu) | ((ub & 0xffu) << 8) | ((uc & 0xffu) << 16) | (ud << 24);
.Lf8t_win8a0_a_go:
	s_mov_b32 s58, 0
	v_pk_mul_f32 v[80:81], v[80:81], s[36:37] op_sel_hi:[1,0]
	v_pk_mul_f32 v[82:83], v[82:83], s[36:37] op_sel_hi:[1,0]
	v_pk_mul_f32 v[84:85], v[84:85], s[36:37] op_sel_hi:[1,0]
	v_pk_mul_f32 v[86:87], v[86:87], s[36:37] op_sel_hi:[1,0]
	v_pk_mul_f32 v[88:89], v[88:89], s[36:37] op_sel_hi:[1,0]
	v_pk_mul_f32 v[90:91], v[90:91], s[36:37] op_sel_hi:[1,0]
	v_pk_mul_f32 v[92:93], v[92:93], s[36:37] op_sel_hi:[1,0]
	v_pk_mul_f32 v[94:95], v[94:95], s[36:37] op_sel_hi:[1,0]
	v_pk_mul_f32 v[96:97], v[96:97], s[36:37] op_sel_hi:[1,0]
	v_pk_mul_f32 v[98:99], v[98:99], s[36:37] op_sel_hi:[1,0]
	v_pk_mul_f32 v[100:101], v[100:101], s[36:37] op_sel_hi:[1,0]
	v_pk_mul_f32 v[102:103], v[102:103], s[36:37] op_sel_hi:[1,0]
	v_pk_mul_f32 v[104:105], v[104:105], s[36:37] op_sel_hi:[1,0]
	v_pk_mul_f32 v[106:107], v[106:107], s[36:37] op_sel_hi:[1,0]
	v_pk_mul_f32 v[108:109], v[108:109], s[36:37] op_sel_hi:[1,0]
	v_pk_mul_f32 v[110:111], v[110:111], s[36:37] op_sel_hi:[1,0]
	v_pk_mul_f32 v[112:113], v[112:113], s[36:37] op_sel_hi:[1,0]
	v_pk_mul_f32 v[114:115], v[114:115], s[36:37] op_sel_hi:[1,0]
	v_pk_mul_f32 v[116:117], v[116:117], s[36:37] op_sel_hi:[1,0]
	v_pk_mul_f32 v[118:119], v[118:119], s[36:37] op_sel_hi:[1,0]
	v_pk_mul_f32 v[120:121], v[120:121], s[36:37] op_sel_hi:[1,0]
	v_pk_mul_f32 v[122:123], v[122:123], s[36:37] op_sel_hi:[1,0]
	v_pk_mul_f32 v[124:125], v[124:125], s[36:37] op_sel_hi:[1,0]
	v_pk_mul_f32 v[126:127], v[126:127], s[36:37] op_sel_hi:[1,0]
	v_pk_mul_f32 v[128:129], v[128:129], s[36:37] op_sel_hi:[1,0]
	v_pk_mul_f32 v[130:131], v[130:131], s[36:37] op_sel_hi:[1,0]
	v_pk_mul_f32 v[132:133], v[132:133], s[36:37] op_sel_hi:[1,0]
	v_pk_mul_f32 v[134:135], v[134:135], s[36:37] op_sel_hi:[1,0]
	v_pk_mul_f32 v[136:137], v[136:137], s[36:37] op_sel_hi:[1,0]
	v_pk_mul_f32 v[138:139], v[138:139], s[36:37] op_sel_hi:[1,0]
	v_pk_mul_f32 v[140:141], v[140:141], s[36:37] op_sel_hi:[1,0]
	v_pk_mul_f32 v[142:143], v[142:143], s[36:37] op_sel_hi:[1,0]
	v_med3_f32 v80, v80, s40, v216
	v_med3_f32 v81, v81, s40, v216
	v_med3_f32 v82, v82, s40, v216
	v_med3_f32 v83, v83, s40, v216
	v_med3_f32 v84, v84, s40, v216
	v_med3_f32 v85, v85, s40, v216
	v_med3_f32 v86, v86, s40, v216
	v_med3_f32 v87, v87, s40, v216
	v_med3_f32 v88, v88, s40, v216
	v_med3_f32 v89, v89, s40, v216
	v_med3_f32 v90, v90, s40, v216
	v_med3_f32 v91, v91, s40, v216
	v_med3_f32 v92, v92, s40, v216
	v_med3_f32 v93, v93, s40, v216
	v_med3_f32 v94, v94, s40, v216
	v_med3_f32 v95, v95, s40, v216
	v_med3_f32 v96, v96, s40, v216
	v_med3_f32 v97, v97, s40, v216
	v_med3_f32 v98, v98, s40, v216
	v_med3_f32 v99, v99, s40, v216
	v_med3_f32 v100, v100, s40, v216
	v_med3_f32 v101, v101, s40, v216
	v_med3_f32 v102, v102, s40, v216
	v_med3_f32 v103, v103, s40, v216
	v_med3_f32 v104, v104, s40, v216
	v_med3_f32 v105, v105, s40, v216
	v_med3_f32 v106, v106, s40, v216
	v_med3_f32 v107, v107, s40, v216
	v_med3_f32 v108, v108, s40, v216
	v_med3_f32 v109, v109, s40, v216
	v_med3_f32 v110, v110, s40, v216
	v_med3_f32 v111, v111, s40, v216
	v_med3_f32 v112, v112, s40, v216
	v_med3_f32 v113, v113, s40, v216
	v_med3_f32 v114, v114, s40, v216
	v_med3_f32 v115, v115, s40, v216
	v_med3_f32 v116, v116, s40, v216
	v_med3_f32 v117, v117, s40, v216
	v_med3_f32 v118, v118, s40, v216
	v_med3_f32 v119, v119, s40, v216
	v_med3_f32 v120, v120, s40, v216
	v_med3_f32 v121, v121, s40, v216
	v_med3_f32 v122, v122, s40, v216
	v_med3_f32 v123, v123, s40, v216
	v_med3_f32 v124, v124, s40, v216
	v_med3_f32 v125, v125, s40, v216
	v_med3_f32 v126, v126, s40, v216
	v_med3_f32 v127, v127, s40, v216
	v_med3_f32 v128, v128, s40, v216
	v_med3_f32 v129, v129, s40, v216
	v_med3_f32 v130, v130, s40, v216
	v_med3_f32 v131, v131, s40, v216
	v_med3_f32 v132, v132, s40, v216
	v_med3_f32 v133, v133, s40, v216
	v_med3_f32 v134, v134, s40, v216
	v_med3_f32 v135, v135, s40, v216
	v_med3_f32 v136, v136, s40, v216
	v_med3_f32 v137, v137, s40, v216
	v_med3_f32 v138, v138, s40, v216
	v_med3_f32 v139, v139, s40, v216
	v_med3_f32 v140, v140, s40, v216
	v_med3_f32 v141, v141, s40, v216
	v_med3_f32 v142, v142, s40, v216
	v_med3_f32 v143, v143, s40, v216
	v_pk_add_f32 v[80:81], v[80:81], s[38:39] op_sel_hi:[1,0]
	v_pk_add_f32 v[82:83], v[82:83], s[38:39] op_sel_hi:[1,0]
	v_pk_add_f32 v[84:85], v[84:85], s[38:39] op_sel_hi:[1,0]
	v_pk_add_f32 v[86:87], v[86:87], s[38:39] op_sel_hi:[1,0]
	v_pk_add_f32 v[88:89], v[88:89], s[38:39] op_sel_hi:[1,0]
	v_pk_add_f32 v[90:91], v[90:91], s[38:39] op_sel_hi:[1,0]
	v_pk_add_f32 v[92:93], v[92:93], s[38:39] op_sel_hi:[1,0]
	v_pk_add_f32 v[94:95], v[94:95], s[38:39] op_sel_hi:[1,0]
	v_pk_add_f32 v[96:97], v[96:97], s[38:39] op_sel_hi:[1,0]
	v_pk_add_f32 v[98:99], v[98:99], s[38:39] op_sel_hi:[1,0]
	v_pk_add_f32 v[100:101], v[100:101], s[38:39] op_sel_hi:[1,0]
	v_pk_add_f32 v[102:103], v[102:103], s[38:39] op_sel_hi:[1,0]
	v_pk_add_f32 v[104:105], v[104:105], s[38:39] op_sel_hi:[1,0]
	v_pk_add_f32 v[106:107], v[106:107], s[38:39] op_sel_hi:[1,0]
	v_pk_add_f32 v[108:109], v[108:109], s[38:39] op_sel_hi:[1,0]
	v_pk_add_f32 v[110:111], v[110:111], s[38:39] op_sel_hi:[1,0]
	v_pk_add_f32 v[112:113], v[112:113], s[38:39] op_sel_hi:[1,0]
	v_pk_add_f32 v[114:115], v[114:115], s[38:39] op_sel_hi:[1,0]
	v_pk_add_f32 v[116:117], v[116:117], s[38:39] op_sel_hi:[1,0]
	v_pk_add_f32 v[118:119], v[118:119], s[38:39] op_sel_hi:[1,0]
; #define LAS __attribute__((address_space(3)))
; __device__ __forceinline__ unsigned pk4_f8(float a, float b, float c, float d) { int w = __builtin_amdgcn_cvt_pk_fp8_f32(a, b, 0, false); w = __builtin_amdgcn_cvt_pk_fp8_f32(c, d, w, true); return (unsigned)w; }
; #define LDS_WAIT() asm volatile("s_waitcnt lgkmcnt(0)" ::: "memory")
;     ...
;         for (int j = 0; j < 2; ++j) { const int n = (lane >> 2) + 16 * j; const LAS float* sp = scr + (16 * c) * 33 + n;
;             u32x4 o;
;             if (QI8) { o.x = pk4_i8(sp[0 * 33], sp[1 * 33], sp[2 * 33], sp[3 * 33], scl); o.y = pk4_i8(sp[4 * 33], sp[5 * 33], sp[6 * 33], sp[7 * 33], scl);
;                 o.z = pk4_i8(sp[8 * 33], sp[9 * 33], sp[10 * 33], sp[11 * 33], scl); o.w = pk4_i8(sp[12 * 33], sp[13 * 33], sp[14 * 33], sp[15 * 33], scl); }
;             else {
;             o.x = pk4_f8(sp[0 * 33] * scl, sp[1 * 33] * scl, sp[2 * 33] * scl, sp[3 * 33] * scl); o.y = pk4_f8(sp[4 * 33] * scl, sp[5 * 33] * scl, sp[6 * 33] * scl, sp[7 * 33] * scl);
;             o.z = pk4_f8(sp[8 * 33] * scl, sp[9 * 33] * scl, sp[10 * 33] * scl, sp[11 * 33] * scl); o.w = pk4_f8(sp[12 * 33] * scl, sp[13 * 33] * scl, sp[14 * 33] * scl, sp[15 * 33] * scl); }
;             *(u32x4*)(WT + (size_t)(dr0 + n) * K + k0 + 16 * c) = o; }
;         LDS_WAIT(); asm volatile("" ::: "memory"); }
	v_pk_add_f32 v[120:121], v[120:121], s[38:39] op_sel_hi:[1,0]
	v_pk_add_f32 v[122:123], v[122:123], s[38:39] op_sel_hi:[1,0]
	v_pk_add_f32 v[124:125], v[124:125], s[38:39] op_sel_hi:[1,0]
	v_pk_add_f32 v[126:127], v[126:127], s[38:39] op_sel_hi:[1,0]
	v_pk_add_f32 v[128:129], v[128:129], s[38:39] op_sel_hi:[1,0]
	v_pk_add_f32 v[130:131], v[130:131], s[38:39] op_sel_hi:[1,0]
	v_pk_add_f32 v[132:133], v[132:133], s[38:39] op_sel_hi:[1,0]
	v_pk_add_f32 v[134:135], v[134:135], s[38:39] op_sel_hi:[1,0]
	v_pk_add_f32 v[136:137], v[136:137], s[38:39] op_sel_hi:[1,0]
	v_pk_add_f32 v[138:139], v[138:139], s[38:39] op_sel_hi:[1,0]
	v_pk_add_f32 v[140:141], v[140:141], s[38:39] op_sel_hi:[1,0]
	v_pk_add_f32 v[142:143], v[142:143], s[38:39] op_sel_hi:[1,0]
	v_perm_b32 v204, v84, v80, s41
	v_perm_b32 v205, v92, v88, s41
	v_perm_b32 v184, v205, v204, s42
	v_perm_b32 v204, v100, v96, s41
	v_perm_b32 v205, v108, v104, s41
	v_perm_b32 v185, v205, v204, s42
	v_perm_b32 v204, v116, v112, s41
	v_perm_b32 v205, v124, v120, s41
	v_perm_b32 v186, v205, v204, s42
	v_perm_b32 v204, v132, v128, s41
	v_perm_b32 v205, v140, v136, s41
	v_perm_b32 v187, v205, v204, s42
	v_perm_b32 v204, v85, v81, s41
	v_perm_b32 v205, v93, v89, s41
	v_perm_b32 v188, v205, v204, s42
	v_perm_b32 v204, v101, v97, s41
	v_perm_b32 v205, v109, v105, s41
	v_perm_b32 v189, v205, v204, s42
	v_perm_b32 v204, v117, v113, s41
	v_perm_b32 v205, v125, v121, s41
	v_perm_b32 v190, v205, v204, s42
	v_perm_b32 v204, v133, v129, s41
	v_perm_b32 v205, v141, v137, s41
	v_perm_b32 v191, v205, v204, s42
	v_perm_b32 v204, v86, v82, s41
	v_perm_b32 v205, v94, v90, s41
	v_perm_b32 v192, v205, v204, s42
	v_perm_b32 v204, v102, v98, s41
	v_perm_b32 v205, v110, v106, s41
	v_perm_b32 v193, v205, v204, s42
	v_perm_b32 v204, v118, v114, s41
	v_perm_b32 v205, v126, v122, s41
	v_perm_b32 v194, v205, v204, s42
	v_perm_b32 v204, v134, v130, s41
	v_perm_b32 v205, v142, v138, s41
	v_perm_b32 v195, v205, v204, s42
	v_perm_b32 v204, v87, v83, s41
	v_perm_b32 v205, v95, v91, s41
	v_perm_b32 v196, v205, v204, s42
	v_perm_b32 v204, v103, v99, s41
	v_perm_b32 v205, v111, v107, s41
	v_perm_b32 v197, v205, v204, s42
	v_perm_b32 v204, v119, v115, s41
	v_perm_b32 v205, v127, v123, s41
	v_perm_b32 v198, v205, v204, s42
	v_perm_b32 v204, v135, v131, s41
	v_perm_b32 v205, v143, v139, s41
	v_perm_b32 v199, v205, v204, s42
	ds_write_b128 v213, v[184:187] offset:0
	ds_write_b128 v213, v[188:191] offset:144
	ds_write_b128 v213, v[192:195] offset:288
	ds_write_b128 v213, v[196:199] offset:432
	s_mov_b32 s26, s61
	s_add_i32 s26, s26, s17
	s_mul_i32 s26, s26, 0x1000
	s_add_u32 s26, s26, s60
	s_add_u32 s54, s44, s26
	s_addc_u32 s55, s45, 0
	s_waitcnt lgkmcnt(0)
	s_barrier
	ds_read_b128 v[184:187], v214 offset:0
	ds_read_b128 v[188:191], v214 offset:1152
	ds_read_b128 v[192:195], v214 offset:2304
	ds_read_b128 v[196:199], v214 offset:3456
	s_waitcnt lgkmcnt(3)
	global_store_dwordx4 v215, v[184:187], s[54:55]
	s_add_u32 s54, s54, 0x8000
	s_addc_u32 s55, s55, 0
	s_waitcnt lgkmcnt(2)
	global_store_dwordx4 v215, v[188:191], s[54:55]
	s_add_u32 s54, s54, 0x8000
	s_addc_u32 s55, s55, 0
	s_waitcnt lgkmcnt(1)
	global_store_dwordx4 v215, v[192:195], s[54:55]
	s_add_u32 s54, s54, 0x8000
	s_addc_u32 s55, s55, 0
	s_waitcnt lgkmcnt(0)
	global_store_dwordx4 v215, v[196:199], s[54:55]
	s_mov_b32 s19, s59
	s_cmp_lt_u32 s19, 0x400
	s_cbranch_scc0 .Lf8t_win8a0_end
	s_add_i32 s59, s19, s96
	s_cmp_lt_u32 s59, 0x400
	s_cbranch_scc0 .Lf8t_win8a0_b_nonext
	s_mul_hi_u32 s20, s59, 0x8000000
	s_mul_i32 s21, s20, 32
	s_sub_i32 s21, s59, s21
	s_lshl_b32 s60, s20, 7
	s_lshl_b32 s61, s21, 8
	s_add_i32 s24, s60, s16
	s_mul_i32 s24, s24, 0x16b80
	s_lshl_b32 s25, s61, 2
	s_add_u32 s24, s24, s25
	s_add_u32 s52, s50, s24
	s_addc_u32 s53, s51, 0
	global_load_dwordx4 v[80:83], v212, s[52:53] nt
	s_add_u32 s52, s52, 0x16b80
	s_addc_u32 s53, s53, 0
	global_load_dwordx4 v[84:87], v212, s[52:53] nt
	s_add_u32 s52, s52, 0x16b80
	s_addc_u32 s53, s53, 0
	global_load_dwordx4 v[88:91], v212, s[52:53] nt
	s_add_u32 s52, s52, 0x16b80
	s_addc_u32 s53, s53, 0
	global_load_dwordx4 v[92:95], v212, s[52:53] nt
	s_add_u32 s52, s52, 0x16b80
	s_addc_u32 s53, s53, 0
	global_load_dwordx4 v[96:99], v212, s[52:53] nt
	s_add_u32 s52, s52, 0x16b80
	s_addc_u32 s53, s53, 0
	global_load_dwordx4 v[100:103], v212, s[52:53] nt
	s_add_u32 s52, s52, 0x16b80
	s_addc_u32 s53, s53, 0
	global_load_dwordx4 v[104:107], v212, s[52:53] nt
	s_add_u32 s52, s52, 0x16b80
	s_addc_u32 s53, s53, 0
	global_load_dwordx4 v[108:111], v212, s[52:53] nt
	s_add_u32 s52, s52, 0x16b80
	s_addc_u32 s53, s53, 0
	global_load_dwordx4 v[112:115], v212, s[52:53] nt
	s_add_u32 s52, s52, 0x16b80
	s_addc_u32 s53, s53, 0
	global_load_dwordx4 v[116:119], v212, s[52:53] nt
	s_add_u32 s52, s52, 0x16b80
	s_addc_u32 s53, s53, 0
	global_load_dwordx4 v[120:123], v212, s[52:53] nt
	s_add_u32 s52, s52, 0x16b80
	s_addc_u32 s53, s53, 0
	global_load_dwordx4 v[124:127], v212, s[52:53] nt
	s_add_u32 s52, s52, 0x16b80
	s_addc_u32 s53, s53, 0
	global_load_dwordx4 v[128:131], v212, s[52:53] nt
	s_add_u32 s52, s52, 0x16b80
	s_addc_u32 s53, s53, 0
	global_load_dwordx4 v[132:135], v212, s[52:53] nt
	s_add_u32 s52, s52, 0x16b80
	s_addc_u32 s53, s53, 0
	global_load_dwordx4 v[136:139], v212, s[52:53] nt
	s_add_u32 s52, s52, 0x16b80
	s_addc_u32 s53, s53, 0
	global_load_dwordx4 v[140:143], v212, s[52:53] nt
	s_waitcnt vmcnt(20)
	s_branch .Lf8t_win8a0_b_go

; #define LAS __attribute__((address_space(3)))
;     if (ldw == 0) ldw = N;
;     LAS float* scr = (LAS float*)(F.lds + F.wave * 16384); const int lane = F.lane;
;     const int nblk = N / 32, nitems = (K / 64) * nblk;
;     for (int item = F.gw; item < nitems; item += F.NGW) { const int kb = item / nblk, nb = item % nblk, k0 = 64 * kb, n0 = 32 * nb;
;         int dr0 = n0; if (MAP == 1) { if (n0 < DFF) dr0 = (n0 >> 7) * 256 + (n0 & 127); else { const int uo = n0 - DFF; dr0 = (uo >> 7) * 256 + 128 + (uo & 127); } }
; #pragma unroll 8
;         for (int i = 0; i < 32; ++i) { const int kk = 2 * i + (lane >> 5); scr[kk * 33 + (lane & 31)] = W[(size_t)(k0 + kk) * ldw + n0 + (lane & 31)]; }
; __device__ __forceinline__ void p0_prologue(Frame& F) {
;     ...
;       transpose_f8_matrix<0, true>(F, W, D, 2048, w8 + (size_t)8192 * D, I8_W, ldw);
.LBB0_42:
	s_cmpk_lt_i32 s94, 0x1000
	s_cselect_b64 s[4:5], -1, 0
	s_cmpk_gt_i32 s94, 0xfff
	s_cbranch_scc1 .LBB0_55
	s_barrier
	s_load_dwordx2 s[50:51], s[74:75], 0x58
	v_readlane_b32 s16, v240, 2
	v_lshlrev_b32_e32 v212, 4, v178
	v_mov_b32_e32 v216, 0x42fe0000
	s_mov_b32 s36, 0x44fe0000
	s_mov_b32 s37, 0
	s_mov_b32 s38, 0x4b400000
	s_mov_b32 s39, 0
	s_mov_b32 s40, 0xc2fe0000
	s_mov_b32 s41, 0x0c0c0400
	s_mov_b32 s42, 0x05040100
	s_lshl_b32 s17, s16, 5
	v_mul_u32_u24_e32 v213, 0x240, v178
	s_lshl_b32 s18, s16, 4
	v_add_u32_e32 v213, s18, v213
	v_lshrrev_b32_e32 v204, 3, v178
	v_and_b32_e32 v205, 7, v178
	s_lshl_b32 s18, s16, 5
	v_add_u32_e32 v206, s18, v204
	v_mul_u32_u24_e32 v214, 0x90, v206
	v_lshl_add_u32 v214, v205, 4, v214
	v_mul_u32_u24_e32 v215, 0x1000, v204
	v_lshl_add_u32 v215, v205, 4, v215
	s_lshl_b32 s16, s16, 4
	s_waitcnt lgkmcnt(0)
	s_add_u32 s44, s90, 0x37b00000
	s_addc_u32 s45, s91, 0
	s_mov_b32 s19, s2
	s_cmp_lt_u32 s19, 0x100
	s_cbranch_scc0 .Lf8t_win8bcd0_end
	s_mul_hi_u32 s20, s19, 0x20000000
	s_mul_i32 s21, s20, 8
	s_sub_i32 s21, s19, s21
	s_lshl_b32 s60, s20, 7
	s_lshl_b32 s61, s21, 8
	s_add_i32 s24, s60, s16
	s_mul_i32 s24, s24, 0x16b80
	s_lshl_b32 s25, s61, 2
	s_add_u32 s24, s24, s25
	s_add_u32 s52, s50, s24
	s_addc_u32 s53, s51, 0
	global_load_dwordx4 v[80:83], v212, s[52:53] nt
	s_add_u32 s52, s52, 0x16b80
	s_addc_u32 s53, s53, 0
	global_load_dwordx4 v[84:87], v212, s[52:53] nt
	s_add_u32 s52, s52, 0x16b80
	s_addc_u32 s53, s53, 0
	global_load_dwordx4 v[88:91], v212, s[52:53] nt
	s_add_u32 s52, s52, 0x16b80
	s_addc_u32 s53, s53, 0
	global_load_dwordx4 v[92:95], v212, s[52:53] nt
	s_add_u32 s52, s52, 0x16b80
	s_addc_u32 s53, s53, 0
	global_load_dwordx4 v[96:99], v212, s[52:53] nt
	s_add_u32 s52, s52, 0x16b80
	s_addc_u32 s53, s53, 0
	global_load_dwordx4 v[100:103], v212, s[52:53] nt
	s_add_u32 s52, s52, 0x16b80
	s_addc_u32 s53, s53, 0
	global_load_dwordx4 v[104:107], v212, s[52:53] nt
	s_add_u32 s52, s52, 0x16b80
	s_addc_u32 s53, s53, 0
	global_load_dwordx4 v[108:111], v212, s[52:53] nt
	s_add_u32 s52, s52, 0x16b80
	s_addc_u32 s53, s53, 0
	global_load_dwordx4 v[112:115], v212, s[52:53] nt
	s_add_u32 s52, s52, 0x16b80
	s_addc_u32 s53, s53, 0
	global_load_dwordx4 v[116:119], v212, s[52:53] nt
	s_add_u32 s52, s52, 0x16b80
	s_addc_u32 s53, s53, 0
	global_load_dwordx4 v[120:123], v212, s[52:53] nt
	s_add_u32 s52, s52, 0x16b80
	s_addc_u32 s53, s53, 0
	global_load_dwordx4 v[124:127], v212, s[52:53] nt
	s_add_u32 s52, s52, 0x16b80
	s_addc_u32 s53, s53, 0
	global_load_dwordx4 v[128:131], v212, s[52:53] nt
	s_add_u32 s52, s52, 0x16b80
	s_addc_u32 s53, s53, 0
	global_load_dwordx4 v[132:135], v212, s[52:53] nt
	s_add_u32 s52, s52, 0x16b80
	s_addc_u32 s53, s53, 0
	global_load_dwordx4 v[136:139], v212, s[52:53] nt
	s_add_u32 s52, s52, 0x16b80
	s_addc_u32 s53, s53, 0
	global_load_dwordx4 v[140:143], v212, s[52:53] nt
	s_mov_b32 s58, 1
.Lf8t_win8bcd0_loop:
	s_add_i32 s59, s19, s96
	s_cmp_lt_u32 s59, 0x100
	s_cbranch_scc0 .Lf8t_win8bcd0_a_nonext
	s_mul_hi_u32 s20, s59, 0x20000000
	s_mul_i32 s21, s20, 8
	s_sub_i32 s21, s59, s21
	s_lshl_b32 s62, s20, 7
	s_lshl_b32 s63, s21, 8
	s_add_i32 s24, s62, s16
	s_mul_i32 s24, s24, 0x16b80
	s_lshl_b32 s25, s63, 2
	s_add_u32 s24, s24, s25
	s_add_u32 s52, s50, s24
	s_addc_u32 s53, s51, 0
	global_load_dwordx4 v[16:19], v212, s[52:53] nt
	s_add_u32 s52, s52, 0x16b80
	s_addc_u32 s53, s53, 0
	global_load_dwordx4 v[20:23], v212, s[52:53] nt
	s_add_u32 s52, s52, 0x16b80
	s_addc_u32 s53, s53, 0
	global_load_dwordx4 v[24:27], v212, s[52:53] nt
	s_add_u32 s52, s52, 0x16b80
	s_addc_u32 s53, s53, 0
	global_load_dwordx4 v[28:31], v212, s[52:53] nt
	s_add_u32 s52, s52, 0x16b80
	s_addc_u32 s53, s53, 0
	global_load_dwordx4 v[32:35], v212, s[52:53] nt
	s_add_u32 s52, s52, 0x16b80
	s_addc_u32 s53, s53, 0
	global_load_dwordx4 v[36:39], v212, s[52:53] nt
	s_add_u32 s52, s52, 0x16b80
	s_addc_u32 s53, s53, 0
	global_load_dwordx4 v[40:43], v212, s[52:53] nt
	s_add_u32 s52, s52, 0x16b80
	s_addc_u32 s53, s53, 0
	global_load_dwordx4 v[44:47], v212, s[52:53] nt
	s_add_u32 s52, s52, 0x16b80
	s_addc_u32 s53, s53, 0
	global_load_dwordx4 v[48:51], v212, s[52:53] nt
	s_add_u32 s52, s52, 0x16b80
	s_addc_u32 s53, s53, 0
	global_load_dwordx4 v[52:55], v212, s[52:53] nt
	s_add_u32 s52, s52, 0x16b80
	s_addc_u32 s53, s53, 0
	global_load_dwordx4 v[56:59], v212, s[52:53] nt
	s_add_u32 s52, s52, 0x16b80
	s_addc_u32 s53, s53, 0
	global_load_dwordx4 v[60:63], v212, s[52:53] nt
	s_add_u32 s52, s52, 0x16b80
	s_addc_u32 s53, s53, 0
	global_load_dwordx4 v[64:67], v212, s[52:53] nt
	s_add_u32 s52, s52, 0x16b80
	s_addc_u32 s53, s53, 0
	global_load_dwordx4 v[68:71], v212, s[52:53] nt
	s_add_u32 s52, s52, 0x16b80
	s_addc_u32 s53, s53, 0
	global_load_dwordx4 v[144:147], v212, s[52:53] nt
	s_add_u32 s52, s52, 0x16b80
	s_addc_u32 s53, s53, 0
	global_load_dwordx4 v[148:151], v212, s[52:53] nt
	s_cmp_eq_u32 s58, 1
	s_cbranch_scc1 .Lf8t_win8bcd0_a_first
	s_waitcnt vmcnt(20)
	s_branch .Lf8t_win8bcd0_a_go

; __device__ __forceinline__ unsigned pk4_i8(float a, float b, float c, float d, float s) {
;     const unsigned ua = __float_as_uint(__builtin_amdgcn_fmed3f(a * s, -127.f, 127.f) + 12582912.f), ub = __float_as_uint(__builtin_amdgcn_fmed3f(b * s, -127.f, 127.f) + 12582912.f);
;     const unsigned uc = __float_as_uint(__builtin_amdgcn_fmed3f(c * s, -127.f, 127.f) + 12582912.f), ud = __float_as_uint(__builtin_amdgcn_fmed3f(d * s, -127.f, 127.f) + 12582912.f);
;     return (ua & 0xffu) | ((ub & 0xffu) << 8) | ((uc & 0xffu) << 16) | (ud << 24);
.Lf8t_win8bcd0_a_go:
	s_mov_b32 s58, 0
	v_pk_mul_f32 v[80:81], v[80:81], s[36:37] op_sel_hi:[1,0]
	v_pk_mul_f32 v[82:83], v[82:83], s[36:37] op_sel_hi:[1,0]
	v_pk_mul_f32 v[84:85], v[84:85], s[36:37] op_sel_hi:[1,0]
	v_pk_mul_f32 v[86:87], v[86:87], s[36:37] op_sel_hi:[1,0]
	v_pk_mul_f32 v[88:89], v[88:89], s[36:37] op_sel_hi:[1,0]
	v_pk_mul_f32 v[90:91], v[90:91], s[36:37] op_sel_hi:[1,0]
	v_pk_mul_f32 v[92:93], v[92:93], s[36:37] op_sel_hi:[1,0]
	v_pk_mul_f32 v[94:95], v[94:95], s[36:37] op_sel_hi:[1,0]
	v_pk_mul_f32 v[96:97], v[96:97], s[36:37] op_sel_hi:[1,0]
	v_pk_mul_f32 v[98:99], v[98:99], s[36:37] op_sel_hi:[1,0]
	v_pk_mul_f32 v[100:101], v[100:101], s[36:37] op_sel_hi:[1,0]
	v_pk_mul_f32 v[102:103], v[102:103], s[36:37] op_sel_hi:[1,0]
	v_pk_mul_f32 v[104:105], v[104:105], s[36:37] op_sel_hi:[1,0]
	v_pk_mul_f32 v[106:107], v[106:107], s[36:37] op_sel_hi:[1,0]
	v_pk_mul_f32 v[108:109], v[108:109], s[36:37] op_sel_hi:[1,0]
	v_pk_mul_f32 v[110:111], v[110:111], s[36:37] op_sel_hi:[1,0]
	v_pk_mul_f32 v[112:113], v[112:113], s[36:37] op_sel_hi:[1,0]
	v_pk_mul_f32 v[114:115], v[114:115], s[36:37] op_sel_hi:[1,0]
	v_pk_mul_f32 v[116:117], v[116:117], s[36:37] op_sel_hi:[1,0]
	v_pk_mul_f32 v[118:119], v[118:119], s[36:37] op_sel_hi:[1,0]
	v_pk_mul_f32 v[120:121], v[120:121], s[36:37] op_sel_hi:[1,0]
	v_pk_mul_f32 v[122:123], v[122:123], s[36:37] op_sel_hi:[1,0]
	v_pk_mul_f32 v[124:125], v[124:125], s[36:37] op_sel_hi:[1,0]
	v_pk_mul_f32 v[126:127], v[126:127], s[36:37] op_sel_hi:[1,0]
	v_pk_mul_f32 v[128:129], v[128:129], s[36:37] op_sel_hi:[1,0]
	v_pk_mul_f32 v[130:131], v[130:131], s[36:37] op_sel_hi:[1,0]
	v_pk_mul_f32 v[132:133], v[132:133], s[36:37] op_sel_hi:[1,0]
	v_pk_mul_f32 v[134:135], v[134:135], s[36:37] op_sel_hi:[1,0]
	v_pk_mul_f32 v[136:137], v[136:137], s[36:37] op_sel_hi:[1,0]
	v_pk_mul_f32 v[138:139], v[138:139], s[36:37] op_sel_hi:[1,0]
	v_pk_mul_f32 v[140:141], v[140:141], s[36:37] op_sel_hi:[1,0]
	v_pk_mul_f32 v[142:143], v[142:143], s[36:37] op_sel_hi:[1,0]
	v_med3_f32 v80, v80, s40, v216
	v_med3_f32 v81, v81, s40, v216
	v_med3_f32 v82, v82, s40, v216
	v_med3_f32 v83, v83, s40, v216
	v_med3_f32 v84, v84, s40, v216
	v_med3_f32 v85, v85, s40, v216
	v_med3_f32 v86, v86, s40, v216
	v_med3_f32 v87, v87, s40, v216
	v_med3_f32 v88, v88, s40, v216
	v_med3_f32 v89, v89, s40, v216
	v_med3_f32 v90, v90, s40, v216
	v_med3_f32 v91, v91, s40, v216
	v_med3_f32 v92, v92, s40, v216
	v_med3_f32 v93, v93, s40, v216
	v_med3_f32 v94, v94, s40, v216
	v_med3_f32 v95, v95, s40, v216
	v_med3_f32 v96, v96, s40, v216
	v_med3_f32 v97, v97, s40, v216
	v_med3_f32 v98, v98, s40, v216
	v_med3_f32 v99, v99, s40, v216
	v_med3_f32 v100, v100, s40, v216
	v_med3_f32 v101, v101, s40, v216
	v_med3_f32 v102, v102, s40, v216
	v_med3_f32 v103, v103, s40, v216
	v_med3_f32 v104, v104, s40, v216
	v_med3_f32 v105, v105, s40, v216
	v_med3_f32 v106, v106, s40, v216
	v_med3_f32 v107, v107, s40, v216
	v_med3_f32 v108, v108, s40, v216
	v_med3_f32 v109, v109, s40, v216
	v_med3_f32 v110, v110, s40, v216
	v_med3_f32 v111, v111, s40, v216
	v_med3_f32 v112, v112, s40, v216
	v_med3_f32 v113, v113, s40, v216
	v_med3_f32 v114, v114, s40, v216
	v_med3_f32 v115, v115, s40, v216
	v_med3_f32 v116, v116, s40, v216
	v_med3_f32 v117, v117, s40, v216
	v_med3_f32 v118, v118, s40, v216
	v_med3_f32 v119, v119, s40, v216
	v_med3_f32 v120, v120, s40, v216
	v_med3_f32 v121, v121, s40, v216
	v_med3_f32 v122, v122, s40, v216
	v_med3_f32 v123, v123, s40, v216
	v_med3_f32 v124, v124, s40, v216
	v_med3_f32 v125, v125, s40, v216
	v_med3_f32 v126, v126, s40, v216
	v_med3_f32 v127, v127, s40, v216
	v_med3_f32 v128, v128, s40, v216
	v_med3_f32 v129, v129, s40, v216
	v_med3_f32 v130, v130, s40, v216
	v_med3_f32 v131, v131, s40, v216
	v_med3_f32 v132, v132, s40, v216
	v_med3_f32 v133, v133, s40, v216
	v_med3_f32 v134, v134, s40, v216
	v_med3_f32 v135, v135, s40, v216
	v_med3_f32 v136, v136, s40, v216
	v_med3_f32 v137, v137, s40, v216
	v_med3_f32 v138, v138, s40, v216
	v_med3_f32 v139, v139, s40, v216
	v_med3_f32 v140, v140, s40, v216
	v_med3_f32 v141, v141, s40, v216
	v_med3_f32 v142, v142, s40, v216
	v_med3_f32 v143, v143, s40, v216
	v_pk_add_f32 v[80:81], v[80:81], s[38:39] op_sel_hi:[1,0]
	v_pk_add_f32 v[82:83], v[82:83], s[38:39] op_sel_hi:[1,0]
	v_pk_add_f32 v[84:85], v[84:85], s[38:39] op_sel_hi:[1,0]
	v_pk_add_f32 v[86:87], v[86:87], s[38:39] op_sel_hi:[1,0]
	v_pk_add_f32 v[88:89], v[88:89], s[38:39] op_sel_hi:[1,0]
	v_pk_add_f32 v[90:91], v[90:91], s[38:39] op_sel_hi:[1,0]
	v_pk_add_f32 v[92:93], v[92:93], s[38:39] op_sel_hi:[1,0]
	v_pk_add_f32 v[94:95], v[94:95], s[38:39] op_sel_hi:[1,0]
	v_pk_add_f32 v[96:97], v[96:97], s[38:39] op_sel_hi:[1,0]
	v_pk_add_f32 v[98:99], v[98:99], s[38:39] op_sel_hi:[1,0]
	v_pk_add_f32 v[100:101], v[100:101], s[38:39] op_sel_hi:[1,0]
	v_pk_add_f32 v[102:103], v[102:103], s[38:39] op_sel_hi:[1,0]
	v_pk_add_f32 v[104:105], v[104:105], s[38:39] op_sel_hi:[1,0]
	v_pk_add_f32 v[106:107], v[106:107], s[38:39] op_sel_hi:[1,0]
	v_pk_add_f32 v[108:109], v[108:109], s[38:39] op_sel_hi:[1,0]
	v_pk_add_f32 v[110:111], v[110:111], s[38:39] op_sel_hi:[1,0]
	v_pk_add_f32 v[112:113], v[112:113], s[38:39] op_sel_hi:[1,0]
	v_pk_add_f32 v[114:115], v[114:115], s[38:39] op_sel_hi:[1,0]
	v_pk_add_f32 v[116:117], v[116:117], s[38:39] op_sel_hi:[1,0]
	v_pk_add_f32 v[118:119], v[118:119], s[38:39] op_sel_hi:[1,0]
; #define LAS __attribute__((address_space(3)))
; __device__ __forceinline__ unsigned pk4_f8(float a, float b, float c, float d) { int w = __builtin_amdgcn_cvt_pk_fp8_f32(a, b, 0, false); w = __builtin_amdgcn_cvt_pk_fp8_f32(c, d, w, true); return (unsigned)w; }
; #define LDS_WAIT() asm volatile("s_waitcnt lgkmcnt(0)" ::: "memory")
;     ...
;         for (int j = 0; j < 2; ++j) { const int n = (lane >> 2) + 16 * j; const LAS float* sp = scr + (16 * c) * 33 + n;
;             u32x4 o;
;             if (QI8) { o.x = pk4_i8(sp[0 * 33], sp[1 * 33], sp[2 * 33], sp[3 * 33], scl); o.y = pk4_i8(sp[4 * 33], sp[5 * 33], sp[6 * 33], sp[7 * 33], scl);
;                 o.z = pk4_i8(sp[8 * 33], sp[9 * 33], sp[10 * 33], sp[11 * 33], scl); o.w = pk4_i8(sp[12 * 33], sp[13 * 33], sp[14 * 33], sp[15 * 33], scl); }
;             else {
;             o.x = pk4_f8(sp[0 * 33] * scl, sp[1 * 33] * scl, sp[2 * 33] * scl, sp[3 * 33] * scl); o.y = pk4_f8(sp[4 * 33] * scl, sp[5 * 33] * scl, sp[6 * 33] * scl, sp[7 * 33] * scl);
;             o.z = pk4_f8(sp[8 * 33] * scl, sp[9 * 33] * scl, sp[10 * 33] * scl, sp[11 * 33] * scl); o.w = pk4_f8(sp[12 * 33] * scl, sp[13 * 33] * scl, sp[14 * 33] * scl, sp[15 * 33] * scl); }
;             *(u32x4*)(WT + (size_t)(dr0 + n) * K + k0 + 16 * c) = o; }
;         LDS_WAIT(); asm volatile("" ::: "memory"); }
	v_pk_add_f32 v[120:121], v[120:121], s[38:39] op_sel_hi:[1,0]
	v_pk_add_f32 v[122:123], v[122:123], s[38:39] op_sel_hi:[1,0]
	v_pk_add_f32 v[124:125], v[124:125], s[38:39] op_sel_hi:[1,0]
	v_pk_add_f32 v[126:127], v[126:127], s[38:39] op_sel_hi:[1,0]
	v_pk_add_f32 v[128:129], v[128:129], s[38:39] op_sel_hi:[1,0]
	v_pk_add_f32 v[130:131], v[130:131], s[38:39] op_sel_hi:[1,0]
	v_pk_add_f32 v[132:133], v[132:133], s[38:39] op_sel_hi:[1,0]
	v_pk_add_f32 v[134:135], v[134:135], s[38:39] op_sel_hi:[1,0]
	v_pk_add_f32 v[136:137], v[136:137], s[38:39] op_sel_hi:[1,0]
	v_pk_add_f32 v[138:139], v[138:139], s[38:39] op_sel_hi:[1,0]
	v_pk_add_f32 v[140:141], v[140:141], s[38:39] op_sel_hi:[1,0]
	v_pk_add_f32 v[142:143], v[142:143], s[38:39] op_sel_hi:[1,0]
	v_perm_b32 v204, v84, v80, s41
	v_perm_b32 v205, v92, v88, s41
	v_perm_b32 v184, v205, v204, s42
	v_perm_b32 v204, v100, v96, s41
	v_perm_b32 v205, v108, v104, s41
	v_perm_b32 v185, v205, v204, s42
	v_perm_b32 v204, v116, v112, s41
	v_perm_b32 v205, v124, v120, s41
	v_perm_b32 v186, v205, v204, s42
	v_perm_b32 v204, v132, v128, s41
	v_perm_b32 v205, v140, v136, s41
	v_perm_b32 v187, v205, v204, s42
	v_perm_b32 v204, v85, v81, s41
	v_perm_b32 v205, v93, v89, s41
	v_perm_b32 v188, v205, v204, s42
	v_perm_b32 v204, v101, v97, s41
	v_perm_b32 v205, v109, v105, s41
	v_perm_b32 v189, v205, v204, s42
	v_perm_b32 v204, v117, v113, s41
	v_perm_b32 v205, v125, v121, s41
	v_perm_b32 v190, v205, v204, s42
	v_perm_b32 v204, v133, v129, s41
	v_perm_b32 v205, v141, v137, s41
	v_perm_b32 v191, v205, v204, s42
	v_perm_b32 v204, v86, v82, s41
	v_perm_b32 v205, v94, v90, s41
	v_perm_b32 v192, v205, v204, s42
	v_perm_b32 v204, v102, v98, s41
	v_perm_b32 v205, v110, v106, s41
	v_perm_b32 v193, v205, v204, s42
	v_perm_b32 v204, v118, v114, s41
	v_perm_b32 v205, v126, v122, s41
	v_perm_b32 v194, v205, v204, s42
	v_perm_b32 v204, v134, v130, s41
	v_perm_b32 v205, v142, v138, s41
	v_perm_b32 v195, v205, v204, s42
	v_perm_b32 v204, v87, v83, s41
	v_perm_b32 v205, v95, v91, s41
	v_perm_b32 v196, v205, v204, s42
	v_perm_b32 v204, v103, v99, s41
	v_perm_b32 v205, v111, v107, s41
	v_perm_b32 v197, v205, v204, s42
	v_perm_b32 v204, v119, v115, s41
	v_perm_b32 v205, v127, v123, s41
	v_perm_b32 v198, v205, v204, s42
	v_perm_b32 v204, v135, v131, s41
	v_perm_b32 v205, v143, v139, s41
	v_perm_b32 v199, v205, v204, s42
	ds_write_b128 v213, v[184:187] offset:0
	ds_write_b128 v213, v[188:191] offset:144
	ds_write_b128 v213, v[192:195] offset:288
	ds_write_b128 v213, v[196:199] offset:432
	s_mov_b32 s26, s61
	s_add_i32 s26, s26, s17
	s_mul_i32 s26, s26, 0x1000
	s_add_u32 s26, s26, s60
	s_add_u32 s54, s44, s26
	s_addc_u32 s55, s45, 0
	s_waitcnt lgkmcnt(0)
	s_barrier
	ds_read_b128 v[184:187], v214 offset:0
	ds_read_b128 v[188:191], v214 offset:1152
	ds_read_b128 v[192:195], v214 offset:2304
	ds_read_b128 v[196:199], v214 offset:3456
	s_waitcnt lgkmcnt(3)
	global_store_dwordx4 v215, v[184:187], s[54:55]
	s_add_u32 s54, s54, 0x8000
	s_addc_u32 s55, s55, 0
	s_waitcnt lgkmcnt(2)
	global_store_dwordx4 v215, v[188:191], s[54:55]
	s_add_u32 s54, s54, 0x8000
	s_addc_u32 s55, s55, 0
	s_waitcnt lgkmcnt(1)
	global_store_dwordx4 v215, v[192:195], s[54:55]
	s_add_u32 s54, s54, 0x8000
	s_addc_u32 s55, s55, 0
	s_waitcnt lgkmcnt(0)
	global_store_dwordx4 v215, v[196:199], s[54:55]
	s_mov_b32 s19, s59
	s_cmp_lt_u32 s19, 0x100
	s_cbranch_scc0 .Lf8t_win8bcd0_end
	s_add_i32 s59, s19, s96
	s_cmp_lt_u32 s59, 0x100
	s_cbranch_scc0 .Lf8t_win8bcd0_b_nonext
	s_mul_hi_u32 s20, s59, 0x20000000
	s_mul_i32 s21, s20, 8
	s_sub_i32 s21, s59, s21
	s_lshl_b32 s60, s20, 7
	s_lshl_b32 s61, s21, 8
	s_add_i32 s24, s60, s16
	s_mul_i32 s24, s24, 0x16b80
	s_lshl_b32 s25, s61, 2
	s_add_u32 s24, s24, s25
	s_add_u32 s52, s50, s24
	s_addc_u32 s53, s51, 0
	global_load_dwordx4 v[80:83], v212, s[52:53] nt
	s_add_u32 s52, s52, 0x16b80
	s_addc_u32 s53, s53, 0
	global_load_dwordx4 v[84:87], v212, s[52:53] nt
	s_add_u32 s52, s52, 0x16b80
	s_addc_u32 s53, s53, 0
	global_load_dwordx4 v[88:91], v212, s[52:53] nt
	s_add_u32 s52, s52, 0x16b80
	s_addc_u32 s53, s53, 0
	global_load_dwordx4 v[92:95], v212, s[52:53] nt
	s_add_u32 s52, s52, 0x16b80
	s_addc_u32 s53, s53, 0
	global_load_dwordx4 v[96:99], v212, s[52:53] nt
	s_add_u32 s52, s52, 0x16b80
	s_addc_u32 s53, s53, 0
	global_load_dwordx4 v[100:103], v212, s[52:53] nt
	s_add_u32 s52, s52, 0x16b80
	s_addc_u32 s53, s53, 0
	global_load_dwordx4 v[104:107], v212, s[52:53] nt
	s_add_u32 s52, s52, 0x16b80
	s_addc_u32 s53, s53, 0
	global_load_dwordx4 v[108:111], v212, s[52:53] nt
	s_add_u32 s52, s52, 0x16b80
	s_addc_u32 s53, s53, 0
	global_load_dwordx4 v[112:115], v212, s[52:53] nt
	s_add_u32 s52, s52, 0x16b80
	s_addc_u32 s53, s53, 0
	global_load_dwordx4 v[116:119], v212, s[52:53] nt
	s_add_u32 s52, s52, 0x16b80
	s_addc_u32 s53, s53, 0
	global_load_dwordx4 v[120:123], v212, s[52:53] nt
	s_add_u32 s52, s52, 0x16b80
	s_addc_u32 s53, s53, 0
	global_load_dwordx4 v[124:127], v212, s[52:53] nt
	s_add_u32 s52, s52, 0x16b80
	s_addc_u32 s53, s53, 0
	global_load_dwordx4 v[128:131], v212, s[52:53] nt
	s_add_u32 s52, s52, 0x16b80
	s_addc_u32 s53, s53, 0
	global_load_dwordx4 v[132:135], v212, s[52:53] nt
	s_add_u32 s52, s52, 0x16b80
	s_addc_u32 s53, s53, 0
	global_load_dwordx4 v[136:139], v212, s[52:53] nt
	s_add_u32 s52, s52, 0x16b80
	s_addc_u32 s53, s53, 0
	global_load_dwordx4 v[140:143], v212, s[52:53] nt
	s_waitcnt vmcnt(20)
	s_branch .Lf8t_win8bcd0_b_go

; #define LAS __attribute__((address_space(3)))
;     if (ldw == 0) ldw = N;
;     LAS float* scr = (LAS float*)(F.lds + F.wave * 16384); const int lane = F.lane;
;     const int nblk = N / 32, nitems = (K / 64) * nblk;
;     for (int item = F.gw; item < nitems; item += F.NGW) { const int kb = item / nblk, nb = item % nblk, k0 = 64 * kb, n0 = 32 * nb;
;         int dr0 = n0; if (MAP == 1) { if (n0 < DFF) dr0 = (n0 >> 7) * 256 + (n0 & 127); else { const int uo = n0 - DFF; dr0 = (uo >> 7) * 256 + 128 + (uo & 127); } }
; #pragma unroll 8
;         for (int i = 0; i < 32; ++i) { const int kk = 2 * i + (lane >> 5); scr[kk * 33 + (lane & 31)] = W[(size_t)(k0 + kk) * ldw + n0 + (lane & 31)]; }
; __device__ __forceinline__ void p0_prologue(Frame& F) {
;     ...
;       transpose_f8_matrix<0, true>(F, W + 6144, D, 2048, w8 + (size_t)10240 * D, I8_W, ldw);
;       transpose_f8_matrix<0, true>(F, W + 8192, D, 2048, w8 + (size_t)12288 * D, I8_W, ldw); }
.Lf8t_win8bcd0_end:
	s_waitcnt vmcnt(0) lgkmcnt(0)
	s_barrier
	s_barrier
	s_load_dwordx2 s[50:51], s[74:75], 0x58
	v_readlane_b32 s16, v240, 2
	v_lshlrev_b32_e32 v212, 4, v178
	v_mov_b32_e32 v216, 0x42fe0000
	s_mov_b32 s36, 0x44fe0000
	s_mov_b32 s37, 0
	s_mov_b32 s38, 0x4b400000
	s_mov_b32 s39, 0
	s_mov_b32 s40, 0xc2fe0000
	s_mov_b32 s41, 0x0c0c0400
	s_mov_b32 s42, 0x05040100
	s_lshl_b32 s17, s16, 5
	v_mul_u32_u24_e32 v213, 0x240, v178
	s_lshl_b32 s18, s16, 4
	v_add_u32_e32 v213, s18, v213
	v_lshrrev_b32_e32 v204, 3, v178
	v_and_b32_e32 v205, 7, v178
	s_lshl_b32 s18, s16, 5
	v_add_u32_e32 v206, s18, v204
	v_mul_u32_u24_e32 v214, 0x90, v206
	v_lshl_add_u32 v214, v205, 4, v214
	v_mul_u32_u24_e32 v215, 0x1000, v204
	v_lshl_add_u32 v215, v205, 4, v215
	s_lshl_b32 s16, s16, 4
	s_waitcnt lgkmcnt(0)
	s_add_u32 s50, s50, 0x6000
	s_addc_u32 s51, s51, 0
	s_add_u32 s44, s90, 0x38300000
	s_addc_u32 s45, s91, 0
	s_mov_b32 s19, s2
	s_cmp_lt_u32 s19, 0x200
	s_cbranch_scc0 .Lf8t_win8bcd1_end
	s_mul_hi_u32 s20, s19, 0x10000000
	s_mul_i32 s21, s20, 16
	s_sub_i32 s21, s19, s21
	s_lshl_b32 s60, s20, 7
	s_lshl_b32 s61, s21, 8
	s_add_i32 s24, s60, s16
	s_mul_i32 s24, s24, 0x16b80
	s_lshl_b32 s25, s61, 2
	s_add_u32 s24, s24, s25
	s_add_u32 s52, s50, s24
	s_addc_u32 s53, s51, 0
	global_load_dwordx4 v[80:83], v212, s[52:53] nt
	s_add_u32 s52, s52, 0x16b80
	s_addc_u32 s53, s53, 0
	global_load_dwordx4 v[84:87], v212, s[52:53] nt
	s_add_u32 s52, s52, 0x16b80
	s_addc_u32 s53, s53, 0
	global_load_dwordx4 v[88:91], v212, s[52:53] nt
	s_add_u32 s52, s52, 0x16b80
	s_addc_u32 s53, s53, 0
	global_load_dwordx4 v[92:95], v212, s[52:53] nt
	s_add_u32 s52, s52, 0x16b80
	s_addc_u32 s53, s53, 0
	global_load_dwordx4 v[96:99], v212, s[52:53] nt
	s_add_u32 s52, s52, 0x16b80
	s_addc_u32 s53, s53, 0
	global_load_dwordx4 v[100:103], v212, s[52:53] nt
	s_add_u32 s52, s52, 0x16b80
	s_addc_u32 s53, s53, 0
	global_load_dwordx4 v[104:107], v212, s[52:53] nt
	s_add_u32 s52, s52, 0x16b80
	s_addc_u32 s53, s53, 0
	global_load_dwordx4 v[108:111], v212, s[52:53] nt
	s_add_u32 s52, s52, 0x16b80
	s_addc_u32 s53, s53, 0
	global_load_dwordx4 v[112:115], v212, s[52:53] nt
	s_add_u32 s52, s52, 0x16b80
	s_addc_u32 s53, s53, 0
	global_load_dwordx4 v[116:119], v212, s[52:53] nt
	s_add_u32 s52, s52, 0x16b80
	s_addc_u32 s53, s53, 0
	global_load_dwordx4 v[120:123], v212, s[52:53] nt
	s_add_u32 s52, s52, 0x16b80
	s_addc_u32 s53, s53, 0
	global_load_dwordx4 v[124:127], v212, s[52:53] nt
	s_add_u32 s52, s52, 0x16b80
	s_addc_u32 s53, s53, 0
	global_load_dwordx4 v[128:131], v212, s[52:53] nt
	s_add_u32 s52, s52, 0x16b80
	s_addc_u32 s53, s53, 0
	global_load_dwordx4 v[132:135], v212, s[52:53] nt
	s_add_u32 s52, s52, 0x16b80
	s_addc_u32 s53, s53, 0
	global_load_dwordx4 v[136:139], v212, s[52:53] nt
	s_add_u32 s52, s52, 0x16b80
	s_addc_u32 s53, s53, 0
	global_load_dwordx4 v[140:143], v212, s[52:53] nt
	s_mov_b32 s58, 1
.Lf8t_win8bcd1_loop:
	s_add_i32 s59, s19, s96
	s_cmp_lt_u32 s59, 0x200
	s_cbranch_scc0 .Lf8t_win8bcd1_a_nonext
	s_mul_hi_u32 s20, s59, 0x10000000
	s_mul_i32 s21, s20, 16
	s_sub_i32 s21, s59, s21
	s_lshl_b32 s62, s20, 7
	s_lshl_b32 s63, s21, 8
	s_add_i32 s24, s62, s16
	s_mul_i32 s24, s24, 0x16b80
	s_lshl_b32 s25, s63, 2
	s_add_u32 s24, s24, s25
	s_add_u32 s52, s50, s24
	s_addc_u32 s53, s51, 0
	global_load_dwordx4 v[16:19], v212, s[52:53] nt
	s_add_u32 s52, s52, 0x16b80
	s_addc_u32 s53, s53, 0
	global_load_dwordx4 v[20:23], v212, s[52:53] nt
	s_add_u32 s52, s52, 0x16b80
	s_addc_u32 s53, s53, 0
	global_load_dwordx4 v[24:27], v212, s[52:53] nt
	s_add_u32 s52, s52, 0x16b80
	s_addc_u32 s53, s53, 0
	global_load_dwordx4 v[28:31], v212, s[52:53] nt
	s_add_u32 s52, s52, 0x16b80
	s_addc_u32 s53, s53, 0
	global_load_dwordx4 v[32:35], v212, s[52:53] nt
	s_add_u32 s52, s52, 0x16b80
	s_addc_u32 s53, s53, 0
	global_load_dwordx4 v[36:39], v212, s[52:53] nt
	s_add_u32 s52, s52, 0x16b80
	s_addc_u32 s53, s53, 0
	global_load_dwordx4 v[40:43], v212, s[52:53] nt
	s_add_u32 s52, s52, 0x16b80
	s_addc_u32 s53, s53, 0
	global_load_dwordx4 v[44:47], v212, s[52:53] nt
	s_add_u32 s52, s52, 0x16b80
	s_addc_u32 s53, s53, 0
	global_load_dwordx4 v[48:51], v212, s[52:53] nt
	s_add_u32 s52, s52, 0x16b80
	s_addc_u32 s53, s53, 0
	global_load_dwordx4 v[52:55], v212, s[52:53] nt
	s_add_u32 s52, s52, 0x16b80
	s_addc_u32 s53, s53, 0
	global_load_dwordx4 v[56:59], v212, s[52:53] nt
	s_add_u32 s52, s52, 0x16b80
	s_addc_u32 s53, s53, 0
	global_load_dwordx4 v[60:63], v212, s[52:53] nt
	s_add_u32 s52, s52, 0x16b80
	s_addc_u32 s53, s53, 0
	global_load_dwordx4 v[64:67], v212, s[52:53] nt
	s_add_u32 s52, s52, 0x16b80
	s_addc_u32 s53, s53, 0
	global_load_dwordx4 v[68:71], v212, s[52:53] nt
	s_add_u32 s52, s52, 0x16b80
	s_addc_u32 s53, s53, 0
	global_load_dwordx4 v[144:147], v212, s[52:53] nt
	s_add_u32 s52, s52, 0x16b80
	s_addc_u32 s53, s53, 0
	global_load_dwordx4 v[148:151], v212, s[52:53] nt
	s_cmp_eq_u32 s58, 1
	s_cbranch_scc1 .Lf8t_win8bcd1_a_first
	s_waitcnt vmcnt(20)
	s_branch .Lf8t_win8bcd1_a_go

; __device__ __forceinline__ unsigned pk4_i8(float a, float b, float c, float d, float s) {
;     const unsigned ua = __float_as_uint(__builtin_amdgcn_fmed3f(a * s, -127.f, 127.f) + 12582912.f), ub = __float_as_uint(__builtin_amdgcn_fmed3f(b * s, -127.f, 127.f) + 12582912.f);
;     const unsigned uc = __float_as_uint(__builtin_amdgcn_fmed3f(c * s, -127.f, 127.f) + 12582912.f), ud = __float_as_uint(__builtin_amdgcn_fmed3f(d * s, -127.f, 127.f) + 12582912.f);
;     return (ua & 0xffu) | ((ub & 0xffu) << 8) | ((uc & 0xffu) << 16) | (ud << 24);
.Lf8t_win8bcd1_a_go:
	s_mov_b32 s58, 0
	v_pk_mul_f32 v[80:81], v[80:81], s[36:37] op_sel_hi:[1,0]
	v_pk_mul_f32 v[82:83], v[82:83], s[36:37] op_sel_hi:[1,0]
	v_pk_mul_f32 v[84:85], v[84:85], s[36:37] op_sel_hi:[1,0]
	v_pk_mul_f32 v[86:87], v[86:87], s[36:37] op_sel_hi:[1,0]
	v_pk_mul_f32 v[88:89], v[88:89], s[36:37] op_sel_hi:[1,0]
	v_pk_mul_f32 v[90:91], v[90:91], s[36:37] op_sel_hi:[1,0]
	v_pk_mul_f32 v[92:93], v[92:93], s[36:37] op_sel_hi:[1,0]
	v_pk_mul_f32 v[94:95], v[94:95], s[36:37] op_sel_hi:[1,0]
	v_pk_mul_f32 v[96:97], v[96:97], s[36:37] op_sel_hi:[1,0]
	v_pk_mul_f32 v[98:99], v[98:99], s[36:37] op_sel_hi:[1,0]
	v_pk_mul_f32 v[100:101], v[100:101], s[36:37] op_sel_hi:[1,0]
	v_pk_mul_f32 v[102:103], v[102:103], s[36:37] op_sel_hi:[1,0]
	v_pk_mul_f32 v[104:105], v[104:105], s[36:37] op_sel_hi:[1,0]
	v_pk_mul_f32 v[106:107], v[106:107], s[36:37] op_sel_hi:[1,0]
	v_pk_mul_f32 v[108:109], v[108:109], s[36:37] op_sel_hi:[1,0]
	v_pk_mul_f32 v[110:111], v[110:111], s[36:37] op_sel_hi:[1,0]
	v_pk_mul_f32 v[112:113], v[112:113], s[36:37] op_sel_hi:[1,0]
	v_pk_mul_f32 v[114:115], v[114:115], s[36:37] op_sel_hi:[1,0]
	v_pk_mul_f32 v[116:117], v[116:117], s[36:37] op_sel_hi:[1,0]
	v_pk_mul_f32 v[118:119], v[118:119], s[36:37] op_sel_hi:[1,0]
	v_pk_mul_f32 v[120:121], v[120:121], s[36:37] op_sel_hi:[1,0]
	v_pk_mul_f32 v[122:123], v[122:123], s[36:37] op_sel_hi:[1,0]
	v_pk_mul_f32 v[124:125], v[124:125], s[36:37] op_sel_hi:[1,0]
	v_pk_mul_f32 v[126:127], v[126:127], s[36:37] op_sel_hi:[1,0]
	v_pk_mul_f32 v[128:129], v[128:129], s[36:37] op_sel_hi:[1,0]
	v_pk_mul_f32 v[130:131], v[130:131], s[36:37] op_sel_hi:[1,0]
	v_pk_mul_f32 v[132:133], v[132:133], s[36:37] op_sel_hi:[1,0]
	v_pk_mul_f32 v[134:135], v[134:135], s[36:37] op_sel_hi:[1,0]
	v_pk_mul_f32 v[136:137], v[136:137], s[36:37] op_sel_hi:[1,0]
	v_pk_mul_f32 v[138:139], v[138:139], s[36:37] op_sel_hi:[1,0]
	v_pk_mul_f32 v[140:141], v[140:141], s[36:37] op_sel_hi:[1,0]
	v_pk_mul_f32 v[142:143], v[142:143], s[36:37] op_sel_hi:[1,0]
	v_med3_f32 v80, v80, s40, v216
	v_med3_f32 v81, v81, s40, v216
	v_med3_f32 v82, v82, s40, v216
	v_med3_f32 v83, v83, s40, v216
	v_med3_f32 v84, v84, s40, v216
	v_med3_f32 v85, v85, s40, v216
	v_med3_f32 v86, v86, s40, v216
	v_med3_f32 v87, v87, s40, v216
	v_med3_f32 v88, v88, s40, v216
	v_med3_f32 v89, v89, s40, v216
	v_med3_f32 v90, v90, s40, v216
	v_med3_f32 v91, v91, s40, v216
	v_med3_f32 v92, v92, s40, v216
	v_med3_f32 v93, v93, s40, v216
	v_med3_f32 v94, v94, s40, v216
	v_med3_f32 v95, v95, s40, v216
	v_med3_f32 v96, v96, s40, v216
	v_med3_f32 v97, v97, s40, v216
	v_med3_f32 v98, v98, s40, v216
	v_med3_f32 v99, v99, s40, v216
	v_med3_f32 v100, v100, s40, v216
	v_med3_f32 v101, v101, s40, v216
	v_med3_f32 v102, v102, s40, v216
	v_med3_f32 v103, v103, s40, v216
	v_med3_f32 v104, v104, s40, v216
	v_med3_f32 v105, v105, s40, v216
	v_med3_f32 v106, v106, s40, v216
	v_med3_f32 v107, v107, s40, v216
	v_med3_f32 v108, v108, s40, v216
	v_med3_f32 v109, v109, s40, v216
	v_med3_f32 v110, v110, s40, v216
	v_med3_f32 v111, v111, s40, v216
	v_med3_f32 v112, v112, s40, v216
	v_med3_f32 v113, v113, s40, v216
	v_med3_f32 v114, v114, s40, v216
	v_med3_f32 v115, v115, s40, v216
	v_med3_f32 v116, v116, s40, v216
	v_med3_f32 v117, v117, s40, v216
	v_med3_f32 v118, v118, s40, v216
	v_med3_f32 v119, v119, s40, v216
	v_med3_f32 v120, v120, s40, v216
	v_med3_f32 v121, v121, s40, v216
	v_med3_f32 v122, v122, s40, v216
	v_med3_f32 v123, v123, s40, v216
	v_med3_f32 v124, v124, s40, v216
	v_med3_f32 v125, v125, s40, v216
	v_med3_f32 v126, v126, s40, v216
	v_med3_f32 v127, v127, s40, v216
	v_med3_f32 v128, v128, s40, v216
	v_med3_f32 v129, v129, s40, v216
	v_med3_f32 v130, v130, s40, v216
	v_med3_f32 v131, v131, s40, v216
	v_med3_f32 v132, v132, s40, v216
	v_med3_f32 v133, v133, s40, v216
	v_med3_f32 v134, v134, s40, v216
	v_med3_f32 v135, v135, s40, v216
	v_med3_f32 v136, v136, s40, v216
	v_med3_f32 v137, v137, s40, v216
	v_med3_f32 v138, v138, s40, v216
	v_med3_f32 v139, v139, s40, v216
	v_med3_f32 v140, v140, s40, v216
	v_med3_f32 v141, v141, s40, v216
	v_med3_f32 v142, v142, s40, v216
	v_med3_f32 v143, v143, s40, v216
	v_pk_add_f32 v[80:81], v[80:81], s[38:39] op_sel_hi:[1,0]
	v_pk_add_f32 v[82:83], v[82:83], s[38:39] op_sel_hi:[1,0]
	v_pk_add_f32 v[84:85], v[84:85], s[38:39] op_sel_hi:[1,0]
	v_pk_add_f32 v[86:87], v[86:87], s[38:39] op_sel_hi:[1,0]
	v_pk_add_f32 v[88:89], v[88:89], s[38:39] op_sel_hi:[1,0]
	v_pk_add_f32 v[90:91], v[90:91], s[38:39] op_sel_hi:[1,0]
	v_pk_add_f32 v[92:93], v[92:93], s[38:39] op_sel_hi:[1,0]
	v_pk_add_f32 v[94:95], v[94:95], s[38:39] op_sel_hi:[1,0]
	v_pk_add_f32 v[96:97], v[96:97], s[38:39] op_sel_hi:[1,0]
	v_pk_add_f32 v[98:99], v[98:99], s[38:39] op_sel_hi:[1,0]
	v_pk_add_f32 v[100:101], v[100:101], s[38:39] op_sel_hi:[1,0]
	v_pk_add_f32 v[102:103], v[102:103], s[38:39] op_sel_hi:[1,0]
	v_pk_add_f32 v[104:105], v[104:105], s[38:39] op_sel_hi:[1,0]
	v_pk_add_f32 v[106:107], v[106:107], s[38:39] op_sel_hi:[1,0]
	v_pk_add_f32 v[108:109], v[108:109], s[38:39] op_sel_hi:[1,0]
	v_pk_add_f32 v[110:111], v[110:111], s[38:39] op_sel_hi:[1,0]
	v_pk_add_f32 v[112:113], v[112:113], s[38:39] op_sel_hi:[1,0]
	v_pk_add_f32 v[114:115], v[114:115], s[38:39] op_sel_hi:[1,0]
	v_pk_add_f32 v[116:117], v[116:117], s[38:39] op_sel_hi:[1,0]
	v_pk_add_f32 v[118:119], v[118:119], s[38:39] op_sel_hi:[1,0]
; #define LAS __attribute__((address_space(3)))
; __device__ __forceinline__ unsigned pk4_f8(float a, float b, float c, float d) { int w = __builtin_amdgcn_cvt_pk_fp8_f32(a, b, 0, false); w = __builtin_amdgcn_cvt_pk_fp8_f32(c, d, w, true); return (unsigned)w; }
; #define LDS_WAIT() asm volatile("s_waitcnt lgkmcnt(0)" ::: "memory")
; __device__ __forceinline__ unsigned pk4_i8(float a, float b, float c, float d, float s) {
;     const unsigned ua = __float_as_uint(__builtin_amdgcn_fmed3f(a * s, -127.f, 127.f) + 12582912.f), ub = __float_as_uint(__builtin_amdgcn_fmed3f(b * s, -127.f, 127.f) + 12582912.f);
;     const unsigned uc = __float_as_uint(__builtin_amdgcn_fmed3f(c * s, -127.f, 127.f) + 12582912.f), ud = __float_as_uint(__builtin_amdgcn_fmed3f(d * s, -127.f, 127.f) + 12582912.f);
;     return (ua & 0xffu) | ((ub & 0xffu) << 8) | ((uc & 0xffu) << 16) | (ud << 24);
;     ...
;         for (int j = 0; j < 2; ++j) { const int n = (lane >> 2) + 16 * j; const LAS float* sp = scr + (16 * c) * 33 + n;
;             u32x4 o;
;             if (QI8) { o.x = pk4_i8(sp[0 * 33], sp[1 * 33], sp[2 * 33], sp[3 * 33], scl); o.y = pk4_i8(sp[4 * 33], sp[5 * 33], sp[6 * 33], sp[7 * 33], scl);
;                 o.z = pk4_i8(sp[8 * 33], sp[9 * 33], sp[10 * 33], sp[11 * 33], scl); o.w = pk4_i8(sp[12 * 33], sp[13 * 33], sp[14 * 33], sp[15 * 33], scl); }
;             else {
;             o.x = pk4_f8(sp[0 * 33] * scl, sp[1 * 33] * scl, sp[2 * 33] * scl, sp[3 * 33] * scl); o.y = pk4_f8(sp[4 * 33] * scl, sp[5 * 33] * scl, sp[6 * 33] * scl, sp[7 * 33] * scl);
;             o.z = pk4_f8(sp[8 * 33] * scl, sp[9 * 33] * scl, sp[10 * 33] * scl, sp[11 * 33] * scl); o.w = pk4_f8(sp[12 * 33] * scl, sp[13 * 33] * scl, sp[14 * 33] * scl, sp[15 * 33] * scl); }
;             *(u32x4*)(WT + (size_t)(dr0 + n) * K + k0 + 16 * c) = o; }
;         LDS_WAIT(); asm volatile("" ::: "memory"); }
	v_pk_add_f32 v[120:121], v[120:121], s[38:39] op_sel_hi:[1,0]
	v_pk_add_f32 v[122:123], v[122:123], s[38:39] op_sel_hi:[1,0]
	v_pk_add_f32 v[124:125], v[124:125], s[38:39] op_sel_hi:[1,0]
	v_pk_add_f32 v[126:127], v[126:127], s[38:39] op_sel_hi:[1,0]
	v_pk_add_f32 v[128:129], v[128:129], s[38:39] op_sel_hi:[1,0]
	v_pk_add_f32 v[130:131], v[130:131], s[38:39] op_sel_hi:[1,0]
	v_pk_add_f32 v[132:133], v[132:133], s[38:39] op_sel_hi:[1,0]
	v_pk_add_f32 v[134:135], v[134:135], s[38:39] op_sel_hi:[1,0]
	v_pk_add_f32 v[136:137], v[136:137], s[38:39] op_sel_hi:[1,0]
	v_pk_add_f32 v[138:139], v[138:139], s[38:39] op_sel_hi:[1,0]
	v_pk_add_f32 v[140:141], v[140:141], s[38:39] op_sel_hi:[1,0]
	v_pk_add_f32 v[142:143], v[142:143], s[38:39] op_sel_hi:[1,0]
	v_perm_b32 v204, v84, v80, s41
	v_perm_b32 v205, v92, v88, s41
	v_perm_b32 v184, v205, v204, s42
	v_perm_b32 v204, v100, v96, s41
	v_perm_b32 v205, v108, v104, s41
	v_perm_b32 v185, v205, v204, s42
	v_perm_b32 v204, v116, v112, s41
	v_perm_b32 v205, v124, v120, s41
	v_perm_b32 v186, v205, v204, s42
	v_perm_b32 v204, v132, v128, s41
	v_perm_b32 v205, v140, v136, s41
	v_perm_b32 v187, v205, v204, s42
	v_perm_b32 v204, v85, v81, s41
	v_perm_b32 v205, v93, v89, s41
	v_perm_b32 v188, v205, v204, s42
	v_perm_b32 v204, v101, v97, s41
	v_perm_b32 v205, v109, v105, s41
	v_perm_b32 v189, v205, v204, s42
	v_perm_b32 v204, v117, v113, s41
	v_perm_b32 v205, v125, v121, s41
	v_perm_b32 v190, v205, v204, s42
	v_perm_b32 v204, v133, v129, s41
	v_perm_b32 v205, v141, v137, s41
	v_perm_b32 v191, v205, v204, s42
	v_perm_b32 v204, v86, v82, s41
	v_perm_b32 v205, v94, v90, s41
	v_perm_b32 v192, v205, v204, s42
	v_perm_b32 v204, v102, v98, s41
	v_perm_b32 v205, v110, v106, s41
	v_perm_b32 v193, v205, v204, s42
	v_perm_b32 v204, v118, v114, s41
	v_perm_b32 v205, v126, v122, s41
	v_perm_b32 v194, v205, v204, s42
	v_perm_b32 v204, v134, v130, s41
	v_perm_b32 v205, v142, v138, s41
	v_perm_b32 v195, v205, v204, s42
	v_perm_b32 v204, v87, v83, s41
	v_perm_b32 v205, v95, v91, s41
	v_perm_b32 v196, v205, v204, s42
	v_perm_b32 v204, v103, v99, s41
	v_perm_b32 v205, v111, v107, s41
	v_perm_b32 v197, v205, v204, s42
	v_perm_b32 v204, v119, v115, s41
	v_perm_b32 v205, v127, v123, s41
	v_perm_b32 v198, v205, v204, s42
	v_perm_b32 v204, v135, v131, s41
	v_perm_b32 v205, v143, v139, s41
	v_perm_b32 v199, v205, v204, s42
	ds_write_b128 v213, v[184:187] offset:0
	ds_write_b128 v213, v[188:191] offset:144
	ds_write_b128 v213, v[192:195] offset:288
	ds_write_b128 v213, v[196:199] offset:432
	s_mov_b32 s26, s61
	s_add_i32 s26, s26, s17
	s_mul_i32 s26, s26, 0x1000
	s_add_u32 s26, s26, s60
	s_add_u32 s54, s44, s26
	s_addc_u32 s55, s45, 0
	s_waitcnt lgkmcnt(0)
	s_barrier
	ds_read_b128 v[184:187], v214 offset:0
	ds_read_b128 v[188:191], v214 offset:1152
	ds_read_b128 v[192:195], v214 offset:2304
	ds_read_b128 v[196:199], v214 offset:3456
	s_waitcnt lgkmcnt(3)
	global_store_dwordx4 v215, v[184:187], s[54:55]
	s_add_u32 s54, s54, 0x8000
	s_addc_u32 s55, s55, 0
	s_waitcnt lgkmcnt(2)
	global_store_dwordx4 v215, v[188:191], s[54:55]
	s_add_u32 s54, s54, 0x8000
	s_addc_u32 s55, s55, 0
	s_waitcnt lgkmcnt(1)
	global_store_dwordx4 v215, v[192:195], s[54:55]
	s_add_u32 s54, s54, 0x8000
	s_addc_u32 s55, s55, 0
	s_waitcnt lgkmcnt(0)
	global_store_dwordx4 v215, v[196:199], s[54:55]
	s_mov_b32 s19, s59
	s_cmp_lt_u32 s19, 0x200
	s_cbranch_scc0 .Lf8t_win8bcd1_end
	s_add_i32 s59, s19, s96
	s_cmp_lt_u32 s59, 0x200
	s_cbranch_scc0 .Lf8t_win8bcd1_b_nonext
	s_mul_hi_u32 s20, s59, 0x10000000
	s_mul_i32 s21, s20, 16
	s_sub_i32 s21, s59, s21
	s_lshl_b32 s60, s20, 7
	s_lshl_b32 s61, s21, 8
	s_add_i32 s24, s60, s16
	s_mul_i32 s24, s24, 0x16b80
	s_lshl_b32 s25, s61, 2
	s_add_u32 s24, s24, s25
	s_add_u32 s52, s50, s24
	s_addc_u32 s53, s51, 0
	global_load_dwordx4 v[80:83], v212, s[52:53] nt
	s_add_u32 s52, s52, 0x16b80
	s_addc_u32 s53, s53, 0
	global_load_dwordx4 v[84:87], v212, s[52:53] nt
	s_add_u32 s52, s52, 0x16b80
	s_addc_u32 s53, s53, 0
	global_load_dwordx4 v[88:91], v212, s[52:53] nt
	s_add_u32 s52, s52, 0x16b80
	s_addc_u32 s53, s53, 0
	global_load_dwordx4 v[92:95], v212, s[52:53] nt
	s_add_u32 s52, s52, 0x16b80
	s_addc_u32 s53, s53, 0
	global_load_dwordx4 v[96:99], v212, s[52:53] nt
	s_add_u32 s52, s52, 0x16b80
	s_addc_u32 s53, s53, 0
	global_load_dwordx4 v[100:103], v212, s[52:53] nt
	s_add_u32 s52, s52, 0x16b80
	s_addc_u32 s53, s53, 0
	global_load_dwordx4 v[104:107], v212, s[52:53] nt
	s_add_u32 s52, s52, 0x16b80
	s_addc_u32 s53, s53, 0
	global_load_dwordx4 v[108:111], v212, s[52:53] nt
	s_add_u32 s52, s52, 0x16b80
	s_addc_u32 s53, s53, 0
	global_load_dwordx4 v[112:115], v212, s[52:53] nt
	s_add_u32 s52, s52, 0x16b80
	s_addc_u32 s53, s53, 0
	global_load_dwordx4 v[116:119], v212, s[52:53] nt
	s_add_u32 s52, s52, 0x16b80
	s_addc_u32 s53, s53, 0
	global_load_dwordx4 v[120:123], v212, s[52:53] nt
	s_add_u32 s52, s52, 0x16b80
	s_addc_u32 s53, s53, 0
	global_load_dwordx4 v[124:127], v212, s[52:53] nt
	s_add_u32 s52, s52, 0x16b80
	s_addc_u32 s53, s53, 0
	global_load_dwordx4 v[128:131], v212, s[52:53] nt
	s_add_u32 s52, s52, 0x16b80
	s_addc_u32 s53, s53, 0
	global_load_dwordx4 v[132:135], v212, s[52:53] nt
	s_add_u32 s52, s52, 0x16b80
	s_addc_u32 s53, s53, 0
	global_load_dwordx4 v[136:139], v212, s[52:53] nt
	s_add_u32 s52, s52, 0x16b80
	s_addc_u32 s53, s53, 0
	global_load_dwordx4 v[140:143], v212, s[52:53] nt
	s_waitcnt vmcnt(20)
	s_branch .Lf8t_win8bcd1_b_go

; #define LAS __attribute__((address_space(3)))
; #define LDS_WAIT() asm volatile("s_waitcnt lgkmcnt(0)" ::: "memory")
;     if (ldw == 0) ldw = N;
;     LAS float* scr = (LAS float*)(F.lds + F.wave * 16384); const int lane = F.lane;
;     const int nblk = N / 32, nitems = (K / 64) * nblk;
;     for (int item = F.gw; item < nitems; item += F.NGW) { const int kb = item / nblk, nb = item % nblk, k0 = 64 * kb, n0 = 32 * nb;
;         int dr0 = n0; if (MAP == 1) { if (n0 < DFF) dr0 = (n0 >> 7) * 256 + (n0 & 127); else { const int uo = n0 - DFF; dr0 = (uo >> 7) * 256 + 128 + (uo & 127); } }
; #pragma unroll 8
;         for (int i = 0; i < 32; ++i) { const int kk = 2 * i + (lane >> 5); scr[kk * 33 + (lane & 31)] = W[(size_t)(k0 + kk) * ldw + n0 + (lane & 31)]; }
;         LDS_WAIT(); asm volatile("" ::: "memory");
; __device__ __forceinline__ void p0_prologue(Frame& F) {
;     ...
;     transpose_f8_matrix<0, true>(F, F.in[I_WOUT], D, D, F.ws + WS_WOUT, I8_WOUT);
.LBB0_67:
	s_andn2_b64 vcc, exec, s[6:7]
	s_cbranch_vccnz .LBB0_72
	s_barrier
	s_load_dwordx2 s[50:51], s[74:75], 0xd8
	v_readlane_b32 s16, v240, 2
	v_lshlrev_b32_e32 v212, 4, v178
	v_mov_b32_e32 v216, 0x42fe0000
	s_mov_b32 s36, 0x45559673
	s_mov_b32 s37, 0
	s_mov_b32 s38, 0x4b400000
	s_mov_b32 s39, 0
	s_mov_b32 s40, 0xc2fe0000
	s_mov_b32 s41, 0x0c0c0400
	s_mov_b32 s42, 0x05040100
	s_lshl_b32 s17, s16, 5
	v_mul_u32_u24_e32 v213, 0x240, v178
	s_lshl_b32 s18, s16, 4
	v_add_u32_e32 v213, s18, v213
	v_lshrrev_b32_e32 v204, 3, v178
	v_and_b32_e32 v205, 7, v178
	s_lshl_b32 s18, s16, 5
	v_add_u32_e32 v206, s18, v204
	v_mul_u32_u24_e32 v214, 0x90, v206
	v_lshl_add_u32 v214, v205, 4, v214
	v_mul_u32_u24_e32 v215, 0x1000, v204
	v_lshl_add_u32 v215, v205, 4, v215
	s_lshl_b32 s16, s16, 4
	s_waitcnt lgkmcnt(0)
	s_add_u32 s44, s90, 0x69d00000
	s_addc_u32 s45, s91, 0
	s_mov_b32 s19, s2
	s_cmp_lt_u32 s19, 0x200
	s_cbranch_scc0 .Lf8t_wout0_end
	s_mul_hi_u32 s20, s19, 0x10000000
	s_mul_i32 s21, s20, 16
	s_sub_i32 s21, s19, s21
	s_lshl_b32 s60, s20, 7
	s_lshl_b32 s61, s21, 8
	s_add_i32 s24, s60, s16
	s_mul_i32 s24, s24, 0x4000
	s_lshl_b32 s25, s61, 2
	s_add_u32 s24, s24, s25
	s_add_u32 s52, s50, s24
	s_addc_u32 s53, s51, 0
	global_load_dwordx4 v[80:83], v212, s[52:53] nt
	s_add_u32 s52, s52, 0x4000
	s_addc_u32 s53, s53, 0
	global_load_dwordx4 v[84:87], v212, s[52:53] nt
	s_add_u32 s52, s52, 0x4000
	s_addc_u32 s53, s53, 0
	global_load_dwordx4 v[88:91], v212, s[52:53] nt
	s_add_u32 s52, s52, 0x4000
	s_addc_u32 s53, s53, 0
	global_load_dwordx4 v[92:95], v212, s[52:53] nt
	s_add_u32 s52, s52, 0x4000
	s_addc_u32 s53, s53, 0
	global_load_dwordx4 v[96:99], v212, s[52:53] nt
	s_add_u32 s52, s52, 0x4000
	s_addc_u32 s53, s53, 0
	global_load_dwordx4 v[100:103], v212, s[52:53] nt
	s_add_u32 s52, s52, 0x4000
	s_addc_u32 s53, s53, 0
	global_load_dwordx4 v[104:107], v212, s[52:53] nt
	s_add_u32 s52, s52, 0x4000
	s_addc_u32 s53, s53, 0
	global_load_dwordx4 v[108:111], v212, s[52:53] nt
	s_add_u32 s52, s52, 0x4000
	s_addc_u32 s53, s53, 0
	global_load_dwordx4 v[112:115], v212, s[52:53] nt
	s_add_u32 s52, s52, 0x4000
	s_addc_u32 s53, s53, 0
	global_load_dwordx4 v[116:119], v212, s[52:53] nt
	s_add_u32 s52, s52, 0x4000
	s_addc_u32 s53, s53, 0
	global_load_dwordx4 v[120:123], v212, s[52:53] nt
	s_add_u32 s52, s52, 0x4000
	s_addc_u32 s53, s53, 0
	global_load_dwordx4 v[124:127], v212, s[52:53] nt
	s_add_u32 s52, s52, 0x4000
	s_addc_u32 s53, s53, 0
	global_load_dwordx4 v[128:131], v212, s[52:53] nt
	s_add_u32 s52, s52, 0x4000
	s_addc_u32 s53, s53, 0
	global_load_dwordx4 v[132:135], v212, s[52:53] nt
	s_add_u32 s52, s52, 0x4000
	s_addc_u32 s53, s53, 0
	global_load_dwordx4 v[136:139], v212, s[52:53] nt
	s_add_u32 s52, s52, 0x4000
	s_addc_u32 s53, s53, 0
	global_load_dwordx4 v[140:143], v212, s[52:53] nt
	s_mov_b32 s58, 1
.Lf8t_wout0_loop:
	s_add_i32 s59, s19, s96
	s_cmp_lt_u32 s59, 0x200
	s_cbranch_scc0 .Lf8t_wout0_a_nonext
	s_mul_hi_u32 s20, s59, 0x10000000
	s_mul_i32 s21, s20, 16
	s_sub_i32 s21, s59, s21
	s_lshl_b32 s62, s20, 7
	s_lshl_b32 s63, s21, 8
	s_add_i32 s24, s62, s16
	s_mul_i32 s24, s24, 0x4000
	s_lshl_b32 s25, s63, 2
	s_add_u32 s24, s24, s25
	s_add_u32 s52, s50, s24
	s_addc_u32 s53, s51, 0
	global_load_dwordx4 v[16:19], v212, s[52:53] nt
	s_add_u32 s52, s52, 0x4000
	s_addc_u32 s53, s53, 0
	global_load_dwordx4 v[20:23], v212, s[52:53] nt
	s_add_u32 s52, s52, 0x4000
	s_addc_u32 s53, s53, 0
	global_load_dwordx4 v[24:27], v212, s[52:53] nt
	s_add_u32 s52, s52, 0x4000
	s_addc_u32 s53, s53, 0
	global_load_dwordx4 v[28:31], v212, s[52:53] nt
	s_add_u32 s52, s52, 0x4000
	s_addc_u32 s53, s53, 0
	global_load_dwordx4 v[32:35], v212, s[52:53] nt
	s_add_u32 s52, s52, 0x4000
	s_addc_u32 s53, s53, 0
	global_load_dwordx4 v[36:39], v212, s[52:53] nt
	s_add_u32 s52, s52, 0x4000
	s_addc_u32 s53, s53, 0
	global_load_dwordx4 v[40:43], v212, s[52:53] nt
	s_add_u32 s52, s52, 0x4000
	s_addc_u32 s53, s53, 0
	global_load_dwordx4 v[44:47], v212, s[52:53] nt
	s_add_u32 s52, s52, 0x4000
	s_addc_u32 s53, s53, 0
	global_load_dwordx4 v[48:51], v212, s[52:53] nt
	s_add_u32 s52, s52, 0x4000
	s_addc_u32 s53, s53, 0
	global_load_dwordx4 v[52:55], v212, s[52:53] nt
	s_add_u32 s52, s52, 0x4000
	s_addc_u32 s53, s53, 0
	global_load_dwordx4 v[56:59], v212, s[52:53] nt
	s_add_u32 s52, s52, 0x4000
	s_addc_u32 s53, s53, 0
	global_load_dwordx4 v[60:63], v212, s[52:53] nt
	s_add_u32 s52, s52, 0x4000
	s_addc_u32 s53, s53, 0
	global_load_dwordx4 v[64:67], v212, s[52:53] nt
	s_add_u32 s52, s52, 0x4000
	s_addc_u32 s53, s53, 0
	global_load_dwordx4 v[68:71], v212, s[52:53] nt
	s_add_u32 s52, s52, 0x4000
	s_addc_u32 s53, s53, 0
	global_load_dwordx4 v[144:147], v212, s[52:53] nt
	s_add_u32 s52, s52, 0x4000
	s_addc_u32 s53, s53, 0
	global_load_dwordx4 v[148:151], v212, s[52:53] nt
	s_cmp_eq_u32 s58, 1
	s_cbranch_scc1 .Lf8t_wout0_a_first
	s_waitcnt vmcnt(20)
	s_branch .Lf8t_wout0_a_go

; __device__ __forceinline__ unsigned pk4_i8(float a, float b, float c, float d, float s) {
;     const unsigned ua = __float_as_uint(__builtin_amdgcn_fmed3f(a * s, -127.f, 127.f) + 12582912.f), ub = __float_as_uint(__builtin_amdgcn_fmed3f(b * s, -127.f, 127.f) + 12582912.f);
;     const unsigned uc = __float_as_uint(__builtin_amdgcn_fmed3f(c * s, -127.f, 127.f) + 12582912.f), ud = __float_as_uint(__builtin_amdgcn_fmed3f(d * s, -127.f, 127.f) + 12582912.f);
;     return (ua & 0xffu) | ((ub & 0xffu) << 8) | ((uc & 0xffu) << 16) | (ud << 24);
;     ...
;             if (QI8) { o.x = pk4_i8(sp[0 * 33], sp[1 * 33], sp[2 * 33], sp[3 * 33], scl); o.y = pk4_i8(sp[4 * 33], sp[5 * 33], sp[6 * 33], sp[7 * 33], scl);
;                 o.z = pk4_i8(sp[8 * 33], sp[9 * 33], sp[10 * 33], sp[11 * 33], scl); o.w = pk4_i8(sp[12 * 33], sp[13 * 33], sp[14 * 33], sp[15 * 33], scl); }
.Lf8t_wout0_a_go:
	s_mov_b32 s58, 0
	v_pk_mul_f32 v[80:81], v[80:81], s[36:37] op_sel_hi:[1,0]
	v_pk_mul_f32 v[82:83], v[82:83], s[36:37] op_sel_hi:[1,0]
	v_pk_mul_f32 v[84:85], v[84:85], s[36:37] op_sel_hi:[1,0]
	v_pk_mul_f32 v[86:87], v[86:87], s[36:37] op_sel_hi:[1,0]
	v_pk_mul_f32 v[88:89], v[88:89], s[36:37] op_sel_hi:[1,0]
	v_pk_mul_f32 v[90:91], v[90:91], s[36:37] op_sel_hi:[1,0]
	v_pk_mul_f32 v[92:93], v[92:93], s[36:37] op_sel_hi:[1,0]
	v_pk_mul_f32 v[94:95], v[94:95], s[36:37] op_sel_hi:[1,0]
	v_pk_mul_f32 v[96:97], v[96:97], s[36:37] op_sel_hi:[1,0]
	v_pk_mul_f32 v[98:99], v[98:99], s[36:37] op_sel_hi:[1,0]
	v_pk_mul_f32 v[100:101], v[100:101], s[36:37] op_sel_hi:[1,0]
	v_pk_mul_f32 v[102:103], v[102:103], s[36:37] op_sel_hi:[1,0]
	v_pk_mul_f32 v[104:105], v[104:105], s[36:37] op_sel_hi:[1,0]
	v_pk_mul_f32 v[106:107], v[106:107], s[36:37] op_sel_hi:[1,0]
	v_pk_mul_f32 v[108:109], v[108:109], s[36:37] op_sel_hi:[1,0]
	v_pk_mul_f32 v[110:111], v[110:111], s[36:37] op_sel_hi:[1,0]
	v_pk_mul_f32 v[112:113], v[112:113], s[36:37] op_sel_hi:[1,0]
	v_pk_mul_f32 v[114:115], v[114:115], s[36:37] op_sel_hi:[1,0]
	v_pk_mul_f32 v[116:117], v[116:117], s[36:37] op_sel_hi:[1,0]
	v_pk_mul_f32 v[118:119], v[118:119], s[36:37] op_sel_hi:[1,0]
	v_pk_mul_f32 v[120:121], v[120:121], s[36:37] op_sel_hi:[1,0]
	v_pk_mul_f32 v[122:123], v[122:123], s[36:37] op_sel_hi:[1,0]
	v_pk_mul_f32 v[124:125], v[124:125], s[36:37] op_sel_hi:[1,0]
	v_pk_mul_f32 v[126:127], v[126:127], s[36:37] op_sel_hi:[1,0]
	v_pk_mul_f32 v[128:129], v[128:129], s[36:37] op_sel_hi:[1,0]
	v_pk_mul_f32 v[130:131], v[130:131], s[36:37] op_sel_hi:[1,0]
	v_pk_mul_f32 v[132:133], v[132:133], s[36:37] op_sel_hi:[1,0]
	v_pk_mul_f32 v[134:135], v[134:135], s[36:37] op_sel_hi:[1,0]
	v_pk_mul_f32 v[136:137], v[136:137], s[36:37] op_sel_hi:[1,0]
	v_pk_mul_f32 v[138:139], v[138:139], s[36:37] op_sel_hi:[1,0]
	v_pk_mul_f32 v[140:141], v[140:141], s[36:37] op_sel_hi:[1,0]
	v_pk_mul_f32 v[142:143], v[142:143], s[36:37] op_sel_hi:[1,0]
	v_med3_f32 v80, v80, s40, v216
	v_med3_f32 v81, v81, s40, v216
	v_med3_f32 v82, v82, s40, v216
	v_med3_f32 v83, v83, s40, v216
	v_med3_f32 v84, v84, s40, v216
	v_med3_f32 v85, v85, s40, v216
	v_med3_f32 v86, v86, s40, v216
	v_med3_f32 v87, v87, s40, v216
	v_med3_f32 v88, v88, s40, v216
	v_med3_f32 v89, v89, s40, v216
	v_med3_f32 v90, v90, s40, v216
	v_med3_f32 v91, v91, s40, v216
	v_med3_f32 v92, v92, s40, v216
	v_med3_f32 v93, v93, s40, v216
	v_med3_f32 v94, v94, s40, v216
	v_med3_f32 v95, v95, s40, v216
	v_med3_f32 v96, v96, s40, v216
	v_med3_f32 v97, v97, s40, v216
	v_med3_f32 v98, v98, s40, v216
	v_med3_f32 v99, v99, s40, v216
	v_med3_f32 v100, v100, s40, v216
	v_med3_f32 v101, v101, s40, v216
	v_med3_f32 v102, v102, s40, v216
	v_med3_f32 v103, v103, s40, v216
	v_med3_f32 v104, v104, s40, v216
	v_med3_f32 v105, v105, s40, v216
	v_med3_f32 v106, v106, s40, v216
	v_med3_f32 v107, v107, s40, v216
	v_med3_f32 v108, v108, s40, v216
	v_med3_f32 v109, v109, s40, v216
	v_med3_f32 v110, v110, s40, v216
	v_med3_f32 v111, v111, s40, v216
	v_med3_f32 v112, v112, s40, v216
	v_med3_f32 v113, v113, s40, v216
	v_med3_f32 v114, v114, s40, v216
	v_med3_f32 v115, v115, s40, v216
	v_med3_f32 v116, v116, s40, v216
	v_med3_f32 v117, v117, s40, v216
	v_med3_f32 v118, v118, s40, v216
	v_med3_f32 v119, v119, s40, v216
	v_med3_f32 v120, v120, s40, v216
	v_med3_f32 v121, v121, s40, v216
	v_med3_f32 v122, v122, s40, v216
	v_med3_f32 v123, v123, s40, v216
	v_med3_f32 v124, v124, s40, v216
	v_med3_f32 v125, v125, s40, v216
	v_med3_f32 v126, v126, s40, v216
	v_med3_f32 v127, v127, s40, v216
	v_med3_f32 v128, v128, s40, v216
	v_med3_f32 v129, v129, s40, v216
	v_med3_f32 v130, v130, s40, v216
	v_med3_f32 v131, v131, s40, v216
	v_med3_f32 v132, v132, s40, v216
	v_med3_f32 v133, v133, s40, v216
	v_med3_f32 v134, v134, s40, v216
	v_med3_f32 v135, v135, s40, v216
	v_med3_f32 v136, v136, s40, v216
	v_med3_f32 v137, v137, s40, v216
	v_med3_f32 v138, v138, s40, v216
	v_med3_f32 v139, v139, s40, v216
	v_med3_f32 v140, v140, s40, v216
	v_med3_f32 v141, v141, s40, v216
	v_med3_f32 v142, v142, s40, v216
	v_med3_f32 v143, v143, s40, v216
	v_pk_add_f32 v[80:81], v[80:81], s[38:39] op_sel_hi:[1,0]
	v_pk_add_f32 v[82:83], v[82:83], s[38:39] op_sel_hi:[1,0]
	v_pk_add_f32 v[84:85], v[84:85], s[38:39] op_sel_hi:[1,0]
	v_pk_add_f32 v[86:87], v[86:87], s[38:39] op_sel_hi:[1,0]
	v_pk_add_f32 v[88:89], v[88:89], s[38:39] op_sel_hi:[1,0]
	v_pk_add_f32 v[90:91], v[90:91], s[38:39] op_sel_hi:[1,0]
	v_pk_add_f32 v[92:93], v[92:93], s[38:39] op_sel_hi:[1,0]
	v_pk_add_f32 v[94:95], v[94:95], s[38:39] op_sel_hi:[1,0]
	v_pk_add_f32 v[96:97], v[96:97], s[38:39] op_sel_hi:[1,0]
	v_pk_add_f32 v[98:99], v[98:99], s[38:39] op_sel_hi:[1,0]
	v_pk_add_f32 v[100:101], v[100:101], s[38:39] op_sel_hi:[1,0]
	v_pk_add_f32 v[102:103], v[102:103], s[38:39] op_sel_hi:[1,0]
	v_pk_add_f32 v[104:105], v[104:105], s[38:39] op_sel_hi:[1,0]
	v_pk_add_f32 v[106:107], v[106:107], s[38:39] op_sel_hi:[1,0]
	v_pk_add_f32 v[108:109], v[108:109], s[38:39] op_sel_hi:[1,0]
	v_pk_add_f32 v[110:111], v[110:111], s[38:39] op_sel_hi:[1,0]
	v_pk_add_f32 v[112:113], v[112:113], s[38:39] op_sel_hi:[1,0]
	v_pk_add_f32 v[114:115], v[114:115], s[38:39] op_sel_hi:[1,0]
	v_pk_add_f32 v[116:117], v[116:117], s[38:39] op_sel_hi:[1,0]
	v_pk_add_f32 v[118:119], v[118:119], s[38:39] op_sel_hi:[1,0]
; #define LAS __attribute__((address_space(3)))
; __device__ __forceinline__ unsigned pk4_f8(float a, float b, float c, float d) { int w = __builtin_amdgcn_cvt_pk_fp8_f32(a, b, 0, false); w = __builtin_amdgcn_cvt_pk_fp8_f32(c, d, w, true); return (unsigned)w; }
; #define LDS_WAIT() asm volatile("s_waitcnt lgkmcnt(0)" ::: "memory")
;     ...
;         for (int j = 0; j < 2; ++j) { const int n = (lane >> 2) + 16 * j; const LAS float* sp = scr + (16 * c) * 33 + n;
;             u32x4 o;
;             if (QI8) { o.x = pk4_i8(sp[0 * 33], sp[1 * 33], sp[2 * 33], sp[3 * 33], scl); o.y = pk4_i8(sp[4 * 33], sp[5 * 33], sp[6 * 33], sp[7 * 33], scl);
;                 o.z = pk4_i8(sp[8 * 33], sp[9 * 33], sp[10 * 33], sp[11 * 33], scl); o.w = pk4_i8(sp[12 * 33], sp[13 * 33], sp[14 * 33], sp[15 * 33], scl); }
;             else {
;             o.x = pk4_f8(sp[0 * 33] * scl, sp[1 * 33] * scl, sp[2 * 33] * scl, sp[3 * 33] * scl); o.y = pk4_f8(sp[4 * 33] * scl, sp[5 * 33] * scl, sp[6 * 33] * scl, sp[7 * 33] * scl);
;             o.z = pk4_f8(sp[8 * 33] * scl, sp[9 * 33] * scl, sp[10 * 33] * scl, sp[11 * 33] * scl); o.w = pk4_f8(sp[12 * 33] * scl, sp[13 * 33] * scl, sp[14 * 33] * scl, sp[15 * 33] * scl); }
;             *(u32x4*)(WT + (size_t)(dr0 + n) * K + k0 + 16 * c) = o; }
;         LDS_WAIT(); asm volatile("" ::: "memory"); }
	v_pk_add_f32 v[120:121], v[120:121], s[38:39] op_sel_hi:[1,0]
	v_pk_add_f32 v[122:123], v[122:123], s[38:39] op_sel_hi:[1,0]
	v_pk_add_f32 v[124:125], v[124:125], s[38:39] op_sel_hi:[1,0]
	v_pk_add_f32 v[126:127], v[126:127], s[38:39] op_sel_hi:[1,0]
	v_pk_add_f32 v[128:129], v[128:129], s[38:39] op_sel_hi:[1,0]
	v_pk_add_f32 v[130:131], v[130:131], s[38:39] op_sel_hi:[1,0]
	v_pk_add_f32 v[132:133], v[132:133], s[38:39] op_sel_hi:[1,0]
	v_pk_add_f32 v[134:135], v[134:135], s[38:39] op_sel_hi:[1,0]
	v_pk_add_f32 v[136:137], v[136:137], s[38:39] op_sel_hi:[1,0]
	v_pk_add_f32 v[138:139], v[138:139], s[38:39] op_sel_hi:[1,0]
	v_pk_add_f32 v[140:141], v[140:141], s[38:39] op_sel_hi:[1,0]
	v_pk_add_f32 v[142:143], v[142:143], s[38:39] op_sel_hi:[1,0]
	v_perm_b32 v204, v84, v80, s41
	v_perm_b32 v205, v92, v88, s41
	v_perm_b32 v184, v205, v204, s42
	v_perm_b32 v204, v100, v96, s41
	v_perm_b32 v205, v108, v104, s41
	v_perm_b32 v185, v205, v204, s42
	v_perm_b32 v204, v116, v112, s41
	v_perm_b32 v205, v124, v120, s41
	v_perm_b32 v186, v205, v204, s42
	v_perm_b32 v204, v132, v128, s41
	v_perm_b32 v205, v140, v136, s41
	v_perm_b32 v187, v205, v204, s42
	v_perm_b32 v204, v85, v81, s41
	v_perm_b32 v205, v93, v89, s41
	v_perm_b32 v188, v205, v204, s42
	v_perm_b32 v204, v101, v97, s41
	v_perm_b32 v205, v109, v105, s41
	v_perm_b32 v189, v205, v204, s42
	v_perm_b32 v204, v117, v113, s41
	v_perm_b32 v205, v125, v121, s41
	v_perm_b32 v190, v205, v204, s42
	v_perm_b32 v204, v133, v129, s41
	v_perm_b32 v205, v141, v137, s41
	v_perm_b32 v191, v205, v204, s42
	v_perm_b32 v204, v86, v82, s41
	v_perm_b32 v205, v94, v90, s41
	v_perm_b32 v192, v205, v204, s42
	v_perm_b32 v204, v102, v98, s41
	v_perm_b32 v205, v110, v106, s41
	v_perm_b32 v193, v205, v204, s42
	v_perm_b32 v204, v118, v114, s41
	v_perm_b32 v205, v126, v122, s41
	v_perm_b32 v194, v205, v204, s42
	v_perm_b32 v204, v134, v130, s41
	v_perm_b32 v205, v142, v138, s41
	v_perm_b32 v195, v205, v204, s42
	v_perm_b32 v204, v87, v83, s41
	v_perm_b32 v205, v95, v91, s41
	v_perm_b32 v196, v205, v204, s42
	v_perm_b32 v204, v103, v99, s41
	v_perm_b32 v205, v111, v107, s41
	v_perm_b32 v197, v205, v204, s42
	v_perm_b32 v204, v119, v115, s41
	v_perm_b32 v205, v127, v123, s41
	v_perm_b32 v198, v205, v204, s42
	v_perm_b32 v204, v135, v131, s41
	v_perm_b32 v205, v143, v139, s41
	v_perm_b32 v199, v205, v204, s42
	ds_write_b128 v213, v[184:187] offset:0
	ds_write_b128 v213, v[188:191] offset:144
	ds_write_b128 v213, v[192:195] offset:288
	ds_write_b128 v213, v[196:199] offset:432
	s_mov_b32 s26, s61
	s_add_i32 s26, s26, s17
	s_mul_i32 s26, s26, 0x1000
	s_add_u32 s26, s26, s60
	s_add_u32 s54, s44, s26
	s_addc_u32 s55, s45, 0
	s_waitcnt lgkmcnt(0)
	s_barrier
	ds_read_b128 v[184:187], v214 offset:0
	ds_read_b128 v[188:191], v214 offset:1152
	ds_read_b128 v[192:195], v214 offset:2304
	ds_read_b128 v[196:199], v214 offset:3456
	s_waitcnt lgkmcnt(3)
	global_store_dwordx4 v215, v[184:187], s[54:55]
	s_add_u32 s54, s54, 0x8000
	s_addc_u32 s55, s55, 0
	s_waitcnt lgkmcnt(2)
	global_store_dwordx4 v215, v[188:191], s[54:55]
	s_add_u32 s54, s54, 0x8000
	s_addc_u32 s55, s55, 0
	s_waitcnt lgkmcnt(1)
	global_store_dwordx4 v215, v[192:195], s[54:55]
	s_add_u32 s54, s54, 0x8000
	s_addc_u32 s55, s55, 0
	s_waitcnt lgkmcnt(0)
	global_store_dwordx4 v215, v[196:199], s[54:55]
	s_mov_b32 s19, s59
	s_cmp_lt_u32 s19, 0x200
	s_cbranch_scc0 .Lf8t_wout0_end
	s_add_i32 s59, s19, s96
	s_cmp_lt_u32 s59, 0x200
	s_cbranch_scc0 .Lf8t_wout0_b_nonext
	s_mul_hi_u32 s20, s59, 0x10000000
	s_mul_i32 s21, s20, 16
	s_sub_i32 s21, s59, s21
	s_lshl_b32 s60, s20, 7
	s_lshl_b32 s61, s21, 8
	s_add_i32 s24, s60, s16
	s_mul_i32 s24, s24, 0x4000
	s_lshl_b32 s25, s61, 2
	s_add_u32 s24, s24, s25
	s_add_u32 s52, s50, s24
	s_addc_u32 s53, s51, 0
	global_load_dwordx4 v[80:83], v212, s[52:53] nt
	s_add_u32 s52, s52, 0x4000
	s_addc_u32 s53, s53, 0
	global_load_dwordx4 v[84:87], v212, s[52:53] nt
	s_add_u32 s52, s52, 0x4000
	s_addc_u32 s53, s53, 0
	global_load_dwordx4 v[88:91], v212, s[52:53] nt
	s_add_u32 s52, s52, 0x4000
	s_addc_u32 s53, s53, 0
	global_load_dwordx4 v[92:95], v212, s[52:53] nt
	s_add_u32 s52, s52, 0x4000
	s_addc_u32 s53, s53, 0
	global_load_dwordx4 v[96:99], v212, s[52:53] nt
	s_add_u32 s52, s52, 0x4000
	s_addc_u32 s53, s53, 0
	global_load_dwordx4 v[100:103], v212, s[52:53] nt
	s_add_u32 s52, s52, 0x4000
	s_addc_u32 s53, s53, 0
	global_load_dwordx4 v[104:107], v212, s[52:53] nt
	s_add_u32 s52, s52, 0x4000
	s_addc_u32 s53, s53, 0
	global_load_dwordx4 v[108:111], v212, s[52:53] nt
	s_add_u32 s52, s52, 0x4000
	s_addc_u32 s53, s53, 0
	global_load_dwordx4 v[112:115], v212, s[52:53] nt
	s_add_u32 s52, s52, 0x4000
	s_addc_u32 s53, s53, 0
	global_load_dwordx4 v[116:119], v212, s[52:53] nt
	s_add_u32 s52, s52, 0x4000
	s_addc_u32 s53, s53, 0
	global_load_dwordx4 v[120:123], v212, s[52:53] nt
	s_add_u32 s52, s52, 0x4000
	s_addc_u32 s53, s53, 0
	global_load_dwordx4 v[124:127], v212, s[52:53] nt
	s_add_u32 s52, s52, 0x4000
	s_addc_u32 s53, s53, 0
	global_load_dwordx4 v[128:131], v212, s[52:53] nt
	s_add_u32 s52, s52, 0x4000
	s_addc_u32 s53, s53, 0
	global_load_dwordx4 v[132:135], v212, s[52:53] nt
	s_add_u32 s52, s52, 0x4000
	s_addc_u32 s53, s53, 0
	global_load_dwordx4 v[136:139], v212, s[52:53] nt
	s_add_u32 s52, s52, 0x4000
	s_addc_u32 s53, s53, 0
	global_load_dwordx4 v[140:143], v212, s[52:53] nt
	s_waitcnt vmcnt(20)
	s_branch .Lf8t_wout0_b_go

; #define LAS __attribute__((address_space(3)))
;     if (ldw == 0) ldw = N;
;     LAS float* scr = (LAS float*)(F.lds + F.wave * 16384); const int lane = F.lane;
;     const int nblk = N / 32, nitems = (K / 64) * nblk;
;     for (int item = F.gw; item < nitems; item += F.NGW) { const int kb = item / nblk, nb = item % nblk, k0 = 64 * kb, n0 = 32 * nb;
;         int dr0 = n0; if (MAP == 1) { if (n0 < DFF) dr0 = (n0 >> 7) * 256 + (n0 & 127); else { const int uo = n0 - DFF; dr0 = (uo >> 7) * 256 + 128 + (uo & 127); } }
; #pragma unroll 8
;         for (int i = 0; i < 32; ++i) { const int kk = 2 * i + (lane >> 5); scr[kk * 33 + (lane & 31)] = W[(size_t)(k0 + kk) * ldw + n0 + (lane & 31)]; }
; __global__ void __launch_bounds__(512, 2) fwd_kernel(Params P) {
;     ...
;     transpose_f8_matrix<1, true>(F, P.in[I_F2IN], D, NFF, P.ws + WS_WFI, I8_W);
.LBB0_1170:
	v_readlane_b32 s0, v240, 3
	v_readlane_b32 s1, v240, 4
	v_readlane_b32 s80, v240, 31
	s_andn2_b64 vcc, exec, s[0:1]
	v_lshlrev_b32_e32 v2, 2, v164
	v_readlane_b32 s81, v240, 32
	s_cbranch_vccnz .LBB0_1179
	s_barrier
	s_load_dwordx2 s[50:51], s[74:75], 0xf0
	v_readlane_b32 s16, v240, 2
	v_lshlrev_b32_e32 v212, 4, v178
	v_mov_b32_e32 v216, 0x42fe0000
	s_mov_b32 s36, 0x44fe0000
	s_mov_b32 s37, 0
	s_mov_b32 s38, 0x4b400000
	s_mov_b32 s39, 0
	s_mov_b32 s40, 0xc2fe0000
	s_mov_b32 s41, 0x0c0c0400
	s_mov_b32 s42, 0x05040100
	s_lshl_b32 s17, s16, 5
	s_and_b32 s18, s16, 4
	s_lshl_b32 s18, s18, 5
	s_add_i32 s17, s17, s18
	v_mul_u32_u24_e32 v213, 0x240, v178
	s_lshl_b32 s18, s16, 4
	v_add_u32_e32 v213, s18, v213
	v_lshrrev_b32_e32 v204, 3, v178
	v_and_b32_e32 v205, 7, v178
	s_lshl_b32 s18, s16, 5
	v_add_u32_e32 v206, s18, v204
	v_mul_u32_u24_e32 v214, 0x90, v206
	v_lshl_add_u32 v214, v205, 4, v214
	v_mul_u32_u24_e32 v215, 0x1000, v204
	v_lshl_add_u32 v215, v205, 4, v215
	s_lshl_b32 s16, s16, 4
	s_waitcnt lgkmcnt(0)
	s_add_u32 s44, s90, 0x8300000
	s_addc_u32 s45, s91, 0
	s_mov_b32 s19, s2
	s_cmp_lt_u32 s19, 0xac0
	s_cbranch_scc0 .Lf8t_f2in0_end
	s_mul_hi_u32 s20, s19, 0x2fa0be9
	s_mul_i32 s21, s20, 86
	s_sub_i32 s21, s19, s21
	s_lshl_b32 s60, s20, 7
	s_lshl_b32 s61, s21, 8
	s_add_i32 s24, s60, s16
	s_mul_i32 s24, s24, 0x15800
	s_lshl_b32 s25, s61, 2
	s_add_u32 s24, s24, s25
	s_add_u32 s52, s50, s24
	s_addc_u32 s53, s51, 0
	global_load_dwordx4 v[80:83], v212, s[52:53] nt
	s_add_u32 s52, s52, 0x15800
	s_addc_u32 s53, s53, 0
	global_load_dwordx4 v[84:87], v212, s[52:53] nt
	s_add_u32 s52, s52, 0x15800
	s_addc_u32 s53, s53, 0
	global_load_dwordx4 v[88:91], v212, s[52:53] nt
	s_add_u32 s52, s52, 0x15800
	s_addc_u32 s53, s53, 0
	global_load_dwordx4 v[92:95], v212, s[52:53] nt
	s_add_u32 s52, s52, 0x15800
	s_addc_u32 s53, s53, 0
	global_load_dwordx4 v[96:99], v212, s[52:53] nt
	s_add_u32 s52, s52, 0x15800
	s_addc_u32 s53, s53, 0
	global_load_dwordx4 v[100:103], v212, s[52:53] nt
	s_add_u32 s52, s52, 0x15800
	s_addc_u32 s53, s53, 0
	global_load_dwordx4 v[104:107], v212, s[52:53] nt
	s_add_u32 s52, s52, 0x15800
	s_addc_u32 s53, s53, 0
	global_load_dwordx4 v[108:111], v212, s[52:53] nt
	s_add_u32 s52, s52, 0x15800
	s_addc_u32 s53, s53, 0
	global_load_dwordx4 v[112:115], v212, s[52:53] nt
	s_add_u32 s52, s52, 0x15800
	s_addc_u32 s53, s53, 0
	global_load_dwordx4 v[116:119], v212, s[52:53] nt
	s_add_u32 s52, s52, 0x15800
	s_addc_u32 s53, s53, 0
	global_load_dwordx4 v[120:123], v212, s[52:53] nt
	s_add_u32 s52, s52, 0x15800
	s_addc_u32 s53, s53, 0
	global_load_dwordx4 v[124:127], v212, s[52:53] nt
	s_add_u32 s52, s52, 0x15800
	s_addc_u32 s53, s53, 0
	global_load_dwordx4 v[128:131], v212, s[52:53] nt
	s_add_u32 s52, s52, 0x15800
	s_addc_u32 s53, s53, 0
	global_load_dwordx4 v[132:135], v212, s[52:53] nt
	s_add_u32 s52, s52, 0x15800
	s_addc_u32 s53, s53, 0
	global_load_dwordx4 v[136:139], v212, s[52:53] nt
	s_add_u32 s52, s52, 0x15800
	s_addc_u32 s53, s53, 0
	global_load_dwordx4 v[140:143], v212, s[52:53] nt
	s_mov_b32 s58, 1

; #define LAS __attribute__((address_space(3)))
;     if (ldw == 0) ldw = N;
;     LAS float* scr = (LAS float*)(F.lds + F.wave * 16384); const int lane = F.lane;
;     const int nblk = N / 32, nitems = (K / 64) * nblk;
;     for (int item = F.gw; item < nitems; item += F.NGW) { const int kb = item / nblk, nb = item % nblk, k0 = 64 * kb, n0 = 32 * nb;
;         int dr0 = n0; if (MAP == 1) { if (n0 < DFF) dr0 = (n0 >> 7) * 256 + (n0 & 127); else { const int uo = n0 - DFF; dr0 = (uo >> 7) * 256 + 128 + (uo & 127); } }
; #pragma unroll 8
;         for (int i = 0; i < 32; ++i) { const int kk = 2 * i + (lane >> 5); scr[kk * 33 + (lane & 31)] = W[(size_t)(k0 + kk) * ldw + n0 + (lane & 31)]; }
; __global__ void __launch_bounds__(512, 2) fwd_kernel(Params P) {
;     ...
;     transpose_f8_matrix<0>(F, P.in[I_F2DN], DFF, D, P.ws + WS_WFD, pg8::W8SCALE_DN); }
.LBB0_1179:
	v_readlane_b32 s0, v240, 5
	v_readlane_b32 s1, v240, 6
	s_andn2_b64 vcc, exec, s[0:1]
	s_cbranch_vccnz .LBB0_1184
	s_barrier
	s_load_dwordx2 s[50:51], s[74:75], 0xf8
	v_readlane_b32 s16, v240, 2
	v_lshlrev_b32_e32 v212, 4, v178
	v_mov_b32_e32 v216, 0x42fe0000
	s_mov_b32 s36, 0x43000000
	s_mov_b32 s37, 0
	s_mov_b32 s38, 0x4b400000
	s_mov_b32 s39, 0
	s_mov_b32 s40, 0xc2fe0000
	s_mov_b32 s41, 0x0c0c0400
	s_mov_b32 s42, 0x05040100
	s_lshl_b32 s17, s16, 5
	v_mul_u32_u24_e32 v213, 0x240, v178
	s_lshl_b32 s18, s16, 4
	v_add_u32_e32 v213, s18, v213
	v_lshrrev_b32_e32 v204, 3, v178
	v_and_b32_e32 v205, 7, v178
	s_lshl_b32 s18, s16, 5
	v_add_u32_e32 v206, s18, v204
	v_mul_u32_u24_e32 v214, 0x90, v206
	v_lshl_add_u32 v214, v205, 4, v214
	v_mul_u32_u24_e32 v215, 0x2b00, v204
	v_lshl_add_u32 v215, v205, 4, v215
	s_lshl_b32 s16, s16, 4
	s_waitcnt lgkmcnt(0)
	s_add_u32 s44, s90, 0x12f00000
	s_addc_u32 s45, s91, 0
	s_mov_b32 s19, s2
	s_cmp_lt_u32 s19, 0x560
	s_cbranch_scc0 .Lf8t_f2dn0_end
	s_mul_hi_u32 s20, s19, 0x10000000
	s_mul_i32 s21, s20, 16
	s_sub_i32 s21, s19, s21
	s_lshl_b32 s60, s20, 7
	s_lshl_b32 s61, s21, 8
	s_add_i32 s24, s60, s16
	s_mul_i32 s24, s24, 0x4000
	s_lshl_b32 s25, s61, 2
	s_add_u32 s24, s24, s25
	s_add_u32 s52, s50, s24
	s_addc_u32 s53, s51, 0
	global_load_dwordx4 v[80:83], v212, s[52:53] nt
	s_add_u32 s52, s52, 0x4000
	s_addc_u32 s53, s53, 0
	global_load_dwordx4 v[84:87], v212, s[52:53] nt
	s_add_u32 s52, s52, 0x4000
	s_addc_u32 s53, s53, 0
	global_load_dwordx4 v[88:91], v212, s[52:53] nt
	s_add_u32 s52, s52, 0x4000
	s_addc_u32 s53, s53, 0
	global_load_dwordx4 v[92:95], v212, s[52:53] nt
	s_add_u32 s52, s52, 0x4000
	s_addc_u32 s53, s53, 0
	global_load_dwordx4 v[96:99], v212, s[52:53] nt
	s_add_u32 s52, s52, 0x4000
	s_addc_u32 s53, s53, 0
	global_load_dwordx4 v[100:103], v212, s[52:53] nt
	s_add_u32 s52, s52, 0x4000
	s_addc_u32 s53, s53, 0
	global_load_dwordx4 v[104:107], v212, s[52:53] nt
	s_add_u32 s52, s52, 0x4000
	s_addc_u32 s53, s53, 0
	global_load_dwordx4 v[108:111], v212, s[52:53] nt
	s_add_u32 s52, s52, 0x4000
	s_addc_u32 s53, s53, 0
	global_load_dwordx4 v[112:115], v212, s[52:53] nt
	s_add_u32 s52, s52, 0x4000
	s_addc_u32 s53, s53, 0
	global_load_dwordx4 v[116:119], v212, s[52:53] nt
	s_add_u32 s52, s52, 0x4000
	s_addc_u32 s53, s53, 0
	global_load_dwordx4 v[120:123], v212, s[52:53] nt
	s_add_u32 s52, s52, 0x4000
	s_addc_u32 s53, s53, 0
	global_load_dwordx4 v[124:127], v212, s[52:53] nt
	s_add_u32 s52, s52, 0x4000
	s_addc_u32 s53, s53, 0
	global_load_dwordx4 v[128:131], v212, s[52:53] nt
	s_add_u32 s52, s52, 0x4000
	s_addc_u32 s53, s53, 0
	global_load_dwordx4 v[132:135], v212, s[52:53] nt
	s_add_u32 s52, s52, 0x4000
	s_addc_u32 s53, s53, 0
	global_load_dwordx4 v[136:139], v212, s[52:53] nt
	s_add_u32 s52, s52, 0x4000
	s_addc_u32 s53, s53, 0
	global_load_dwordx4 v[140:143], v212, s[52:53] nt
	s_mov_b32 s58, 1
